# weight-tile conversion second half (all 11 instances): the eight LDS reads of a thread issued together after the barrier with counted waits instead of read-wait-convert-store one at a time
# speedup vs baseline: 1.0139x; 1.0023x over previous
; __device__ __forceinline__ unsigned cvt_pk_bf16(float lo, float hi) { unsigned r; asm volatile("v_cvt_pk_bf16_f32 %0, %1, %2" : "=v"(r) : "v"(lo), "v"(hi)); return r; }
; __device__ void wt_tile(const float* src, int ld, int k0, int n0, bf16_t* dst, int Kdst, const float* kscale, float mul, LAS float* tile, bool rotperm = false, int drow0 = -1) {
;     ...
;     for (int i = 0; i < 16; ++i) { const int k = (tid >> 7) + 4 * i, n = tid & 127; v[i] = src[(size_t)(k0 + k) * ld + n0 + n]; }
; #pragma unroll
;     for (int i = 0; i < 16; ++i) { const int k = (tid >> 7) + 4 * i, n = tid & 127; float x = v[i] * mul; if (kscale) x *= kscale[k0 + k]; tile[k * 129 + n] = x; }
;     __syncthreads();
; #pragma unroll
;     for (int i = 0; i < 8; ++i) { const int n = (tid >> 5) + 16 * i, k2 = (tid & 31) * 2;
;         const float a = tile[k2 * 129 + n], b = tile[(k2 + 1) * 129 + n]; int nn = (drow0 >= 0 ? drow0 : n0) + n; if (rotperm) nn = (nn & ~127) | (2 * (nn & 63) + ((nn >> 6) & 1));
;         *(unsigned*)(dst + (size_t)nn * Kdst + k0 + k2) = cvt_pk_bf16(a, b); }
.LBB0_415:
	s_cmpk_gt_i32 s8, 0x7f
	s_mov_b64 s[6:7], -1
	s_cbranch_scc0 .LBB0_489
	s_cmpk_gt_u32 s8, 0x1df
	s_cbranch_scc0 .LBB0_454
	s_cmpk_gt_u32 s8, 0x33f
	s_cbranch_scc0 .LBB0_419
	s_add_i32 s7, s8, 0xfcc0
	s_and_b32 s6, s7, 0xffff
	s_mul_i32 s6, s6, 0xba2f
	s_lshr_b32 s6, s6, 21
	s_mul_i32 s19, s6, 44
	s_sub_i32 s7, s7, s19
	s_lshl_b32 s7, s7, 6
	v_mov_b32_e32 v6, v162
	v_readlane_b32 s40, v255, 2
	s_and_b32 s7, s7, 0xffc0
	s_lshl_b32 s19, s6, 9
	v_ashrrev_i32_e32 v7, 7, v6
	v_readlane_b32 s44, v255, 6
	v_add_u32_e32 v2, s7, v7
	v_readlane_b32 s45, v255, 7
	s_add_u32 s34, s44, s19
	v_lshlrev_b32_e32 v0, 2, v6
	s_addc_u32 s35, s45, 0
	v_and_b32_e32 v0, 0x1fc, v0
	v_ashrrev_i32_e32 v3, 31, v2
	v_lshl_add_u64 v[4:5], s[34:35], 0, v[0:1]
	v_lshlrev_b64 v[2:3], 12, v[2:3]
	v_lshl_add_u64 v[2:3], v[4:5], 0, v[2:3]
	s_movk_i32 s19, 0x4000
	v_add_co_u32_e32 v4, vcc, s19, v2
	s_mov_b32 s19, 0x8000
	s_nop 0
	v_addc_co_u32_e32 v5, vcc, 0, v3, vcc
	global_load_dword v8, v[2:3], off
	global_load_dword v9, v[4:5], off
	v_add_co_u32_e32 v4, vcc, s19, v2
	s_mov_b32 s19, 0xc000
	s_nop 0
	v_addc_co_u32_e32 v5, vcc, 0, v3, vcc
	global_load_dword v10, v[4:5], off
	v_add_co_u32_e32 v4, vcc, s19, v2
	s_mov_b32 s19, 0x10000
	s_nop 0
	v_addc_co_u32_e32 v5, vcc, 0, v3, vcc
	global_load_dword v11, v[4:5], off
	v_add_co_u32_e32 v4, vcc, s19, v2
	s_mov_b32 s19, 0x14000
	s_nop 0
	v_addc_co_u32_e32 v5, vcc, 0, v3, vcc
	global_load_dword v12, v[4:5], off
	v_add_co_u32_e32 v4, vcc, s19, v2
	s_mov_b32 s19, 0x18000
	s_nop 0
	v_addc_co_u32_e32 v5, vcc, 0, v3, vcc
	global_load_dword v13, v[4:5], off
	v_add_co_u32_e32 v4, vcc, s19, v2
	s_mov_b32 s19, 0x1c000
	s_nop 0
	v_addc_co_u32_e32 v5, vcc, 0, v3, vcc
	global_load_dword v14, v[4:5], off
	v_add_co_u32_e32 v4, vcc, s19, v2
	s_mov_b32 s19, 0x20000
	s_nop 0
	v_addc_co_u32_e32 v5, vcc, 0, v3, vcc
	global_load_dword v15, v[4:5], off
	v_add_co_u32_e32 v4, vcc, s19, v2
	s_mov_b32 s19, 0x24000
	s_nop 0
	v_addc_co_u32_e32 v5, vcc, 0, v3, vcc
	global_load_dword v16, v[4:5], off
	v_add_co_u32_e32 v4, vcc, s19, v2
	s_mov_b32 s19, 0x28000
	s_nop 0
	v_addc_co_u32_e32 v5, vcc, 0, v3, vcc
	global_load_dword v17, v[4:5], off
	v_add_co_u32_e32 v4, vcc, s19, v2
	s_mov_b32 s19, 0x2c000
	s_nop 0
	v_addc_co_u32_e32 v5, vcc, 0, v3, vcc
	global_load_dword v18, v[4:5], off
	v_add_co_u32_e32 v4, vcc, s19, v2
	s_mov_b32 s19, 0x30000
	s_nop 0
	v_addc_co_u32_e32 v5, vcc, 0, v3, vcc
	global_load_dword v19, v[4:5], off
	v_add_co_u32_e32 v4, vcc, s19, v2
	s_mov_b32 s19, 0x34000
	s_nop 0
	v_addc_co_u32_e32 v5, vcc, 0, v3, vcc
	global_load_dword v20, v[4:5], off
	v_add_co_u32_e32 v4, vcc, s19, v2
	s_mov_b32 s19, 0x38000
	s_nop 0
	v_addc_co_u32_e32 v5, vcc, 0, v3, vcc
	global_load_dword v21, v[4:5], off
	v_add_co_u32_e32 v4, vcc, s19, v2
	s_mov_b32 s19, 0x3c000
	s_nop 0
	v_addc_co_u32_e32 v5, vcc, 0, v3, vcc
	v_add_co_u32_e32 v2, vcc, s19, v2
	global_load_dword v4, v[4:5], off
	s_nop 0
	v_addc_co_u32_e32 v3, vcc, 0, v3, vcc
	global_load_dword v2, v[2:3], off
	s_movk_i32 s19, 0x204
	v_mul_lo_u32 v3, v7, s19
	v_add3_u32 v0, 0, v0, v3
	s_waitcnt vmcnt(0)
	ds_write_b32 v0, v8
	s_waitcnt vmcnt(14)
	ds_write_b32 v0, v9 offset:2064
	s_waitcnt vmcnt(13)
	ds_write_b32 v0, v10 offset:4128
	s_waitcnt vmcnt(12)
	ds_write_b32 v0, v11 offset:6192
	s_waitcnt vmcnt(11)
	ds_write_b32 v0, v12 offset:8256
	s_waitcnt vmcnt(10)
	ds_write_b32 v0, v13 offset:10320
	s_waitcnt vmcnt(9)
	ds_write_b32 v0, v14 offset:12384
	s_waitcnt vmcnt(8)
	ds_write_b32 v0, v15 offset:14448
	s_waitcnt vmcnt(7)
	ds_write_b32 v0, v16 offset:16512
	s_waitcnt vmcnt(6)
	ds_write_b32 v0, v17 offset:18576
	s_waitcnt vmcnt(5)
	ds_write_b32 v0, v18 offset:20640
	s_waitcnt vmcnt(4)
	ds_write_b32 v0, v19 offset:22704
	s_waitcnt vmcnt(3)
	ds_write_b32 v0, v20 offset:24768
	s_waitcnt vmcnt(2)
	ds_write_b32 v0, v21 offset:26832
	s_waitcnt vmcnt(1)
	ds_write_b32 v0, v4 offset:28896
	s_waitcnt vmcnt(0)
	ds_write_b32 v0, v2 offset:30960
	v_lshlrev_b32_e32 v0, 1, v6
	s_lshl_b32 s7, s7, 1
	v_and_b32_e32 v0, 62, v0
	s_add_u32 s34, s9, s7
	v_ashrrev_i32_e32 v4, 5, v6
	v_mul_u32_u24_e32 v5, 0x204, v0
	s_addc_u32 s35, s10, 0
	v_lshlrev_b32_e32 v0, 1, v0
	v_lshl_add_u64 v[2:3], s[34:35], 0, v[0:1]
	v_lshlrev_b32_e32 v0, 2, v4
	v_add3_u32 v0, 0, v5, v0
	s_waitcnt lgkmcnt(0)
	s_barrier
	ds_read2_b32 v[112:113], v0 offset1:129
	ds_read2_b32 v[114:115], v0 offset0:16 offset1:145
	ds_read2_b32 v[116:117], v0 offset0:32 offset1:161
	ds_read2_b32 v[118:119], v0 offset0:48 offset1:177
	ds_read2_b32 v[120:121], v0 offset0:64 offset1:193
	ds_read2_b32 v[122:123], v0 offset0:80 offset1:209
	ds_read2_b32 v[124:125], v0 offset0:96 offset1:225
	ds_read2_b32 v[126:127], v0 offset0:112 offset1:241
	v_lshl_add_u32 v6, s6, 7, v4
	s_movk_i32 s19, 0x1600
	s_waitcnt lgkmcnt(7)
	v_cvt_pk_bf16_f32 v7, v112, v113
	v_mad_i64_i32 v[4:5], s[6:7], v6, s19, v[2:3]
	global_store_dword v[4:5], v7, off
	v_add_u32_e32 v7, 16, v6
	s_waitcnt lgkmcnt(6)
	v_cvt_pk_bf16_f32 v8, v114, v115
	v_mad_i64_i32 v[4:5], s[6:7], v7, s19, v[2:3]
	global_store_dword v[4:5], v8, off
	v_add_u32_e32 v7, 32, v6
	s_waitcnt lgkmcnt(5)
	v_cvt_pk_bf16_f32 v8, v116, v117
	v_mad_i64_i32 v[4:5], s[6:7], v7, s19, v[2:3]
	global_store_dword v[4:5], v8, off
	v_add_u32_e32 v7, 48, v6
	s_waitcnt lgkmcnt(4)
	v_cvt_pk_bf16_f32 v8, v118, v119
	v_mad_i64_i32 v[4:5], s[6:7], v7, s19, v[2:3]
	global_store_dword v[4:5], v8, off
	v_add_u32_e32 v7, 64, v6
	s_waitcnt lgkmcnt(3)
	v_cvt_pk_bf16_f32 v8, v120, v121
	v_mad_i64_i32 v[4:5], s[6:7], v7, s19, v[2:3]
	global_store_dword v[4:5], v8, off
	v_add_u32_e32 v7, 0x50, v6
	s_waitcnt lgkmcnt(2)
	v_cvt_pk_bf16_f32 v8, v122, v123
	v_mad_i64_i32 v[4:5], s[6:7], v7, s19, v[2:3]
	global_store_dword v[4:5], v8, off
	v_add_u32_e32 v7, 0x60, v6
	v_add_u32_e32 v6, 0x70, v6
	s_waitcnt lgkmcnt(1)
	v_cvt_pk_bf16_f32 v8, v124, v125
	v_mad_i64_i32 v[4:5], s[6:7], v7, s19, v[2:3]
	v_mad_i64_i32 v[2:3], s[6:7], v6, s19, v[2:3]
	v_readlane_b32 s41, v255, 3
	v_readlane_b32 s42, v255, 4
	v_readlane_b32 s43, v255, 5
	v_readlane_b32 s46, v255, 8
	v_readlane_b32 s47, v255, 9
	v_readlane_b32 s48, v255, 10
	v_readlane_b32 s49, v255, 11
	v_readlane_b32 s50, v255, 12
	v_readlane_b32 s51, v255, 13
	v_readlane_b32 s52, v255, 14
	v_readlane_b32 s53, v255, 15
	v_readlane_b32 s54, v255, 16
	v_readlane_b32 s55, v255, 17
	global_store_dword v[4:5], v8, off
	s_waitcnt lgkmcnt(0)
	v_cvt_pk_bf16_f32 v0, v126, v127
	global_store_dword v[2:3], v0, off
	s_barrier
	s_mov_b64 s[6:7], 0

; __device__ __forceinline__ unsigned cvt_pk_bf16(float lo, float hi) { unsigned r; asm volatile("v_cvt_pk_bf16_f32 %0, %1, %2" : "=v"(r) : "v"(lo), "v"(hi)); return r; }
; __device__ void wt_tile(const float* src, int ld, int k0, int n0, bf16_t* dst, int Kdst, const float* kscale, float mul, LAS float* tile, bool rotperm = false, int drow0 = -1) {
;     ...
;     for (int i = 0; i < 8; ++i) { const int n = (tid >> 5) + 16 * i, k2 = (tid & 31) * 2;
;         const float a = tile[k2 * 129 + n], b = tile[(k2 + 1) * 129 + n]; int nn = (drow0 >= 0 ? drow0 : n0) + n; if (rotperm) nn = (nn & ~127) | (2 * (nn & 63) + ((nn >> 6) & 1));
;         *(unsigned*)(dst + (size_t)nn * Kdst + k0 + k2) = cvt_pk_bf16(a, b); }
.LBB0_452:
	v_lshlrev_b32_e32 v0, 1, v4
	s_lshl_b32 s7, s7, 1
	v_and_b32_e32 v0, 62, v0
	s_add_u32 s34, s11, s7
	v_ashrrev_i32_e32 v5, 5, v4
	v_mul_u32_u24_e32 v4, 0x204, v0
	s_addc_u32 s35, s12, 0
	v_lshlrev_b32_e32 v0, 1, v0
	v_lshl_add_u64 v[2:3], s[34:35], 0, v[0:1]
	v_lshlrev_b32_e32 v0, 2, v5
	v_lshl_add_u32 v8, s6, 8, v5
	v_add3_u32 v0, 0, v4, v0
	v_add_u32_e32 v4, 0x80, v8
	v_ashrrev_i32_e32 v5, 31, v4
	v_lshlrev_b64 v[4:5], 11, v[4:5]
	s_waitcnt vmcnt(0)
	ds_write_b32 v11, v7 offset:30960
	s_waitcnt lgkmcnt(0)
	s_barrier
	ds_read2_b32 v[104:105], v0 offset1:129
	ds_read2_b32 v[106:107], v0 offset0:16 offset1:145
	ds_read2_b32 v[108:109], v0 offset0:32 offset1:161
	ds_read2_b32 v[110:111], v0 offset0:48 offset1:177
	ds_read2_b32 v[112:113], v0 offset0:64 offset1:193
	ds_read2_b32 v[114:115], v0 offset0:80 offset1:209
	ds_read2_b32 v[116:117], v0 offset0:96 offset1:225
	ds_read2_b32 v[118:119], v0 offset0:112 offset1:241
	v_lshl_add_u64 v[4:5], v[2:3], 0, v[4:5]
	s_waitcnt lgkmcnt(7)
	v_cvt_pk_bf16_f32 v6, v104, v105
	global_store_dword v[4:5], v6, off
	v_add_u32_e32 v4, 0x90, v8
	v_ashrrev_i32_e32 v5, 31, v4
	v_lshlrev_b64 v[4:5], 11, v[4:5]
	v_lshl_add_u64 v[4:5], v[2:3], 0, v[4:5]
	s_waitcnt lgkmcnt(6)
	v_cvt_pk_bf16_f32 v6, v106, v107
	global_store_dword v[4:5], v6, off
	v_add_u32_e32 v4, 0xa0, v8
	v_ashrrev_i32_e32 v5, 31, v4
	v_lshlrev_b64 v[4:5], 11, v[4:5]
	v_lshl_add_u64 v[4:5], v[2:3], 0, v[4:5]
	s_waitcnt lgkmcnt(5)
	v_cvt_pk_bf16_f32 v6, v108, v109
	global_store_dword v[4:5], v6, off
	v_add_u32_e32 v4, 0xb0, v8
	v_ashrrev_i32_e32 v5, 31, v4
	v_lshlrev_b64 v[4:5], 11, v[4:5]
	v_lshl_add_u64 v[4:5], v[2:3], 0, v[4:5]
	s_waitcnt lgkmcnt(4)
	v_cvt_pk_bf16_f32 v6, v110, v111
	global_store_dword v[4:5], v6, off
	v_add_u32_e32 v4, 0xc0, v8
	v_ashrrev_i32_e32 v5, 31, v4
	v_lshlrev_b64 v[4:5], 11, v[4:5]
	v_lshl_add_u64 v[4:5], v[2:3], 0, v[4:5]
	s_waitcnt lgkmcnt(3)
	v_cvt_pk_bf16_f32 v6, v112, v113
	global_store_dword v[4:5], v6, off
	v_add_u32_e32 v4, 0xd0, v8
	v_ashrrev_i32_e32 v5, 31, v4
	v_lshlrev_b64 v[4:5], 11, v[4:5]
	v_lshl_add_u64 v[4:5], v[2:3], 0, v[4:5]
	s_waitcnt lgkmcnt(2)
	v_cvt_pk_bf16_f32 v6, v114, v115
	global_store_dword v[4:5], v6, off
	v_add_u32_e32 v4, 0xe0, v8
	v_ashrrev_i32_e32 v5, 31, v4
	v_lshlrev_b64 v[4:5], 11, v[4:5]
	v_lshl_add_u64 v[4:5], v[2:3], 0, v[4:5]
	s_waitcnt lgkmcnt(1)
	v_cvt_pk_bf16_f32 v6, v116, v117
	global_store_dword v[4:5], v6, off
	v_add_u32_e32 v4, 0xf0, v8
	v_ashrrev_i32_e32 v5, 31, v4
	v_lshlrev_b64 v[4:5], 11, v[4:5]
	v_lshl_add_u64 v[2:3], v[2:3], 0, v[4:5]
	s_waitcnt lgkmcnt(0)
	v_cvt_pk_bf16_f32 v0, v118, v119
	global_store_dword v[2:3], v0, off
	s_barrier

; __device__ __forceinline__ unsigned cvt_pk_bf16(float lo, float hi) { unsigned r; asm volatile("v_cvt_pk_bf16_f32 %0, %1, %2" : "=v"(r) : "v"(lo), "v"(hi)); return r; }
; __device__ void wt_tile(const float* src, int ld, int k0, int n0, bf16_t* dst, int Kdst, const float* kscale, float mul, LAS float* tile, bool rotperm = false, int drow0 = -1) {
;     ...
;     for (int i = 0; i < 8; ++i) { const int n = (tid >> 5) + 16 * i, k2 = (tid & 31) * 2;
;         const float a = tile[k2 * 129 + n], b = tile[(k2 + 1) * 129 + n]; int nn = (drow0 >= 0 ? drow0 : n0) + n; if (rotperm) nn = (nn & ~127) | (2 * (nn & 63) + ((nn >> 6) & 1));
;         *(unsigned*)(dst + (size_t)nn * Kdst + k0 + k2) = cvt_pk_bf16(a, b); }
.LBB0_487:
	v_lshlrev_b32_e32 v0, 1, v4
	s_lshl_b32 s7, s7, 1
	v_and_b32_e32 v0, 62, v0
	s_add_u32 s34, s11, s7
	v_ashrrev_i32_e32 v5, 5, v4
	v_mul_u32_u24_e32 v4, 0x204, v0
	s_addc_u32 s35, s12, 0
	v_lshlrev_b32_e32 v0, 1, v0
	v_lshl_add_u64 v[2:3], s[34:35], 0, v[0:1]
	v_lshlrev_b32_e32 v0, 2, v5
	v_add3_u32 v0, 0, v4, v0
	v_lshl_add_u32 v4, s6, 8, v5
	s_waitcnt vmcnt(0)
	ds_write_b32 v11, v7 offset:30960
	s_waitcnt lgkmcnt(0)
	s_barrier
	ds_read2_b32 v[100:101], v0 offset1:129
	ds_read2_b32 v[102:103], v0 offset0:16 offset1:145
	ds_read2_b32 v[104:105], v0 offset0:32 offset1:161
	ds_read2_b32 v[106:107], v0 offset0:48 offset1:177
	ds_read2_b32 v[108:109], v0 offset0:64 offset1:193
	ds_read2_b32 v[110:111], v0 offset0:80 offset1:209
	ds_read2_b32 v[112:113], v0 offset0:96 offset1:225
	ds_read2_b32 v[114:115], v0 offset0:112 offset1:241
	v_ashrrev_i32_e32 v5, 31, v4
	s_waitcnt lgkmcnt(7)
	v_cvt_pk_bf16_f32 v8, v100, v101
	v_lshlrev_b64 v[6:7], 11, v[4:5]
	v_lshl_add_u64 v[6:7], v[2:3], 0, v[6:7]
	global_store_dword v[6:7], v8, off
	v_add_u32_e32 v6, 16, v4
	v_ashrrev_i32_e32 v7, 31, v6
	v_lshlrev_b64 v[6:7], 11, v[6:7]
	v_lshl_add_u64 v[6:7], v[2:3], 0, v[6:7]
	s_waitcnt lgkmcnt(6)
	v_cvt_pk_bf16_f32 v5, v102, v103
	global_store_dword v[6:7], v5, off
	v_add_u32_e32 v6, 32, v4
	v_ashrrev_i32_e32 v7, 31, v6
	v_lshlrev_b64 v[6:7], 11, v[6:7]
	v_lshl_add_u64 v[6:7], v[2:3], 0, v[6:7]
	s_waitcnt lgkmcnt(5)
	v_cvt_pk_bf16_f32 v5, v104, v105
	global_store_dword v[6:7], v5, off
	v_add_u32_e32 v6, 48, v4
	v_ashrrev_i32_e32 v7, 31, v6
	v_lshlrev_b64 v[6:7], 11, v[6:7]
	v_lshl_add_u64 v[6:7], v[2:3], 0, v[6:7]
	s_waitcnt lgkmcnt(4)
	v_cvt_pk_bf16_f32 v5, v106, v107
	global_store_dword v[6:7], v5, off
	v_add_u32_e32 v6, 64, v4
	v_ashrrev_i32_e32 v7, 31, v6
	v_lshlrev_b64 v[6:7], 11, v[6:7]
	v_lshl_add_u64 v[6:7], v[2:3], 0, v[6:7]
	s_waitcnt lgkmcnt(3)
	v_cvt_pk_bf16_f32 v5, v108, v109
	global_store_dword v[6:7], v5, off
	v_add_u32_e32 v6, 0x50, v4
	v_ashrrev_i32_e32 v7, 31, v6
	v_lshlrev_b64 v[6:7], 11, v[6:7]
	v_lshl_add_u64 v[6:7], v[2:3], 0, v[6:7]
	s_waitcnt lgkmcnt(2)
	v_cvt_pk_bf16_f32 v5, v110, v111
	global_store_dword v[6:7], v5, off
	v_add_u32_e32 v6, 0x60, v4
	v_ashrrev_i32_e32 v7, 31, v6
	v_lshlrev_b64 v[6:7], 11, v[6:7]
	s_waitcnt lgkmcnt(1)
	v_cvt_pk_bf16_f32 v5, v112, v113
	v_lshl_add_u64 v[6:7], v[2:3], 0, v[6:7]
	v_add_u32_e32 v4, 0x70, v4
	global_store_dword v[6:7], v5, off
	v_ashrrev_i32_e32 v5, 31, v4
	v_lshlrev_b64 v[4:5], 11, v[4:5]
	v_lshl_add_u64 v[2:3], v[2:3], 0, v[4:5]
	s_waitcnt lgkmcnt(0)
	v_cvt_pk_bf16_f32 v0, v114, v115
	global_store_dword v[2:3], v0, off
	s_barrier

; __device__ __forceinline__ unsigned cvt_pk_bf16(float lo, float hi) { unsigned r; asm volatile("v_cvt_pk_bf16_f32 %0, %1, %2" : "=v"(r) : "v"(lo), "v"(hi)); return r; }
; __device__ void wt_tile(const float* src, int ld, int k0, int n0, bf16_t* dst, int Kdst, const float* kscale, float mul, LAS float* tile, bool rotperm = false, int drow0 = -1) {
;     ...
;     for (int i = 0; i < 16; ++i) { const int k = (tid >> 7) + 4 * i, n = tid & 127; v[i] = src[(size_t)(k0 + k) * ld + n0 + n]; }
; #pragma unroll
;     for (int i = 0; i < 16; ++i) { const int k = (tid >> 7) + 4 * i, n = tid & 127; float x = v[i] * mul; if (kscale) x *= kscale[k0 + k]; tile[k * 129 + n] = x; }
;     __syncthreads();
; #pragma unroll
;     for (int i = 0; i < 8; ++i) { const int n = (tid >> 5) + 16 * i, k2 = (tid & 31) * 2;
;         const float a = tile[k2 * 129 + n], b = tile[(k2 + 1) * 129 + n]; int nn = (drow0 >= 0 ? drow0 : n0) + n; if (rotperm) nn = (nn & ~127) | (2 * (nn & 63) + ((nn >> 6) & 1));
;         *(unsigned*)(dst + (size_t)nn * Kdst + k0 + k2) = cvt_pk_bf16(a, b); }
.LBB0_489:
	s_andn2_b64 vcc, exec, s[6:7]
	s_cbranch_vccnz .LBB0_414
	s_and_b32 s6, s17, 0xffffff80
	v_readlane_b32 s40, v254, 50
	v_mov_b32_e32 v6, v162
	s_ashr_i32 s7, s6, 31
	v_readlane_b32 s44, v254, 54
	v_readlane_b32 s45, v254, 55
	v_readlane_b32 s46, v254, 56
	v_readlane_b32 s47, v254, 57
	v_readlane_b32 s48, v254, 58
	v_readlane_b32 s49, v254, 59
	v_readlane_b32 s50, v254, 60
	v_readlane_b32 s51, v254, 61
	s_and_b32 s19, s15, 0x3c0
	s_lshl_b64 s[34:35], s[6:7], 2
	v_ashrrev_i32_e32 v7, 7, v6
	v_readlane_b32 s52, v254, 62
	v_readlane_b32 s53, v254, 63
	v_readlane_b32 s54, v255, 0
	v_readlane_b32 s55, v255, 1
	s_mov_b64 s[44:45], s[48:49]
	v_add_u32_e32 v2, s19, v7
	s_add_u32 s34, s44, s34
	v_lshlrev_b32_e32 v0, 2, v6
	s_addc_u32 s35, s45, s35
	v_and_b32_e32 v0, 0x1fc, v0
	v_ashrrev_i32_e32 v3, 31, v2
	v_lshl_add_u64 v[4:5], s[34:35], 0, v[0:1]
	v_lshlrev_b64 v[2:3], 12, v[2:3]
	v_lshl_add_u64 v[2:3], v[4:5], 0, v[2:3]
	s_movk_i32 s7, 0x4000
	v_add_co_u32_e32 v4, vcc, s7, v2
	s_mov_b32 s7, 0x8000
	s_nop 0
	v_addc_co_u32_e32 v5, vcc, 0, v3, vcc
	global_load_dword v8, v[2:3], off
	global_load_dword v9, v[4:5], off
	v_add_co_u32_e32 v4, vcc, s7, v2
	s_mov_b32 s7, 0xc000
	s_nop 0
	v_addc_co_u32_e32 v5, vcc, 0, v3, vcc
	global_load_dword v10, v[4:5], off
	v_add_co_u32_e32 v4, vcc, s7, v2
	s_mov_b32 s7, 0x10000
	s_nop 0
	v_addc_co_u32_e32 v5, vcc, 0, v3, vcc
	global_load_dword v11, v[4:5], off
	v_add_co_u32_e32 v4, vcc, s7, v2
	s_mov_b32 s7, 0x14000
	s_nop 0
	v_addc_co_u32_e32 v5, vcc, 0, v3, vcc
	global_load_dword v12, v[4:5], off
	v_add_co_u32_e32 v4, vcc, s7, v2
	s_mov_b32 s7, 0x18000
	s_nop 0
	v_addc_co_u32_e32 v5, vcc, 0, v3, vcc
	global_load_dword v13, v[4:5], off
	v_add_co_u32_e32 v4, vcc, s7, v2
	s_mov_b32 s7, 0x1c000
	s_nop 0
	v_addc_co_u32_e32 v5, vcc, 0, v3, vcc
	global_load_dword v14, v[4:5], off
	v_add_co_u32_e32 v4, vcc, s7, v2
	s_mov_b32 s7, 0x20000
	s_nop 0
	v_addc_co_u32_e32 v5, vcc, 0, v3, vcc
	global_load_dword v15, v[4:5], off
	v_add_co_u32_e32 v4, vcc, s7, v2
	s_mov_b32 s7, 0x24000
	s_nop 0
	v_addc_co_u32_e32 v5, vcc, 0, v3, vcc
	global_load_dword v16, v[4:5], off
	v_add_co_u32_e32 v4, vcc, s7, v2
	s_mov_b32 s7, 0x28000
	s_nop 0
	v_addc_co_u32_e32 v5, vcc, 0, v3, vcc
	global_load_dword v17, v[4:5], off
	v_add_co_u32_e32 v4, vcc, s7, v2
	s_mov_b32 s7, 0x2c000
	s_nop 0
	v_addc_co_u32_e32 v5, vcc, 0, v3, vcc
	global_load_dword v18, v[4:5], off
	v_add_co_u32_e32 v4, vcc, s7, v2
	s_mov_b32 s7, 0x30000
	s_nop 0
	v_addc_co_u32_e32 v5, vcc, 0, v3, vcc
	global_load_dword v19, v[4:5], off
	v_add_co_u32_e32 v4, vcc, s7, v2
	s_mov_b32 s7, 0x34000
	s_nop 0
	v_addc_co_u32_e32 v5, vcc, 0, v3, vcc
	global_load_dword v20, v[4:5], off
	v_add_co_u32_e32 v4, vcc, s7, v2
	s_mov_b32 s7, 0x38000
	s_nop 0
	v_addc_co_u32_e32 v5, vcc, 0, v3, vcc
	global_load_dword v21, v[4:5], off
	v_add_co_u32_e32 v4, vcc, s7, v2
	s_mov_b32 s7, 0x3c000
	s_nop 0
	v_addc_co_u32_e32 v5, vcc, 0, v3, vcc
	v_add_co_u32_e32 v2, vcc, s7, v2
	global_load_dword v4, v[4:5], off
	s_nop 0
	v_addc_co_u32_e32 v3, vcc, 0, v3, vcc
	global_load_dword v2, v[2:3], off
	s_movk_i32 s7, 0x204
	v_mul_lo_u32 v3, v7, s7
	v_add3_u32 v0, 0, v0, v3
	s_waitcnt vmcnt(0)
	ds_write_b32 v0, v8
	s_waitcnt vmcnt(14)
	ds_write_b32 v0, v9 offset:2064
	s_waitcnt vmcnt(13)
	ds_write_b32 v0, v10 offset:4128
	s_waitcnt vmcnt(12)
	ds_write_b32 v0, v11 offset:6192
	s_waitcnt vmcnt(11)
	ds_write_b32 v0, v12 offset:8256
	s_waitcnt vmcnt(10)
	ds_write_b32 v0, v13 offset:10320
	s_waitcnt vmcnt(9)
	ds_write_b32 v0, v14 offset:12384
	s_waitcnt vmcnt(8)
	ds_write_b32 v0, v15 offset:14448
	s_waitcnt vmcnt(7)
	ds_write_b32 v0, v16 offset:16512
	s_waitcnt vmcnt(6)
	ds_write_b32 v0, v17 offset:18576
	s_waitcnt vmcnt(5)
	ds_write_b32 v0, v18 offset:20640
	s_waitcnt vmcnt(4)
	ds_write_b32 v0, v19 offset:22704
	s_waitcnt vmcnt(3)
	ds_write_b32 v0, v20 offset:24768
	s_waitcnt vmcnt(2)
	ds_write_b32 v0, v21 offset:26832
	s_waitcnt vmcnt(1)
	ds_write_b32 v0, v4 offset:28896
	s_waitcnt vmcnt(0)
	ds_write_b32 v0, v2 offset:30960
	v_lshlrev_b32_e32 v0, 1, v6
	s_lshl_b32 s7, s19, 1
	v_and_b32_e32 v0, 62, v0
	s_add_u32 s34, s13, s7
	v_ashrrev_i32_e32 v4, 5, v6
	v_mul_u32_u24_e32 v5, 0x204, v0
	s_addc_u32 s35, s14, 0
	v_lshlrev_b32_e32 v0, 1, v0
	v_lshl_add_u64 v[2:3], s[34:35], 0, v[0:1]
	v_lshlrev_b32_e32 v0, 2, v4
	v_add3_u32 v0, 0, v5, v0
	v_add_u32_e32 v4, s6, v4
	s_waitcnt lgkmcnt(0)
	s_barrier
	ds_read2_b32 v[100:101], v0 offset1:129
	ds_read2_b32 v[102:103], v0 offset0:16 offset1:145
	ds_read2_b32 v[104:105], v0 offset0:32 offset1:161
	ds_read2_b32 v[106:107], v0 offset0:48 offset1:177
	ds_read2_b32 v[108:109], v0 offset0:64 offset1:193
	ds_read2_b32 v[110:111], v0 offset0:80 offset1:209
	ds_read2_b32 v[112:113], v0 offset0:96 offset1:225
	ds_read2_b32 v[114:115], v0 offset0:112 offset1:241
	v_ashrrev_i32_e32 v5, 31, v4
	s_waitcnt lgkmcnt(7)
	v_cvt_pk_bf16_f32 v8, v100, v101
	v_lshlrev_b64 v[6:7], 11, v[4:5]
	v_lshl_add_u64 v[6:7], v[2:3], 0, v[6:7]
	global_store_dword v[6:7], v8, off
	v_add_u32_e32 v6, 16, v4
	v_ashrrev_i32_e32 v7, 31, v6
	v_lshlrev_b64 v[6:7], 11, v[6:7]
	v_lshl_add_u64 v[6:7], v[2:3], 0, v[6:7]
	s_waitcnt lgkmcnt(6)
	v_cvt_pk_bf16_f32 v5, v102, v103
	global_store_dword v[6:7], v5, off
	v_add_u32_e32 v6, 32, v4
	v_ashrrev_i32_e32 v7, 31, v6
	v_lshlrev_b64 v[6:7], 11, v[6:7]
	v_lshl_add_u64 v[6:7], v[2:3], 0, v[6:7]
	s_waitcnt lgkmcnt(5)
	v_cvt_pk_bf16_f32 v5, v104, v105
	global_store_dword v[6:7], v5, off
	v_add_u32_e32 v6, 48, v4
	v_ashrrev_i32_e32 v7, 31, v6
	v_lshlrev_b64 v[6:7], 11, v[6:7]
	v_lshl_add_u64 v[6:7], v[2:3], 0, v[6:7]
	s_waitcnt lgkmcnt(4)
	v_cvt_pk_bf16_f32 v5, v106, v107
	global_store_dword v[6:7], v5, off
	v_add_u32_e32 v6, 64, v4
	v_ashrrev_i32_e32 v7, 31, v6
	v_lshlrev_b64 v[6:7], 11, v[6:7]
	v_lshl_add_u64 v[6:7], v[2:3], 0, v[6:7]
	s_waitcnt lgkmcnt(3)
	v_cvt_pk_bf16_f32 v5, v108, v109
	global_store_dword v[6:7], v5, off
	v_add_u32_e32 v6, 0x50, v4
	v_ashrrev_i32_e32 v7, 31, v6
	v_lshlrev_b64 v[6:7], 11, v[6:7]
	v_lshl_add_u64 v[6:7], v[2:3], 0, v[6:7]
	s_waitcnt lgkmcnt(2)
	v_cvt_pk_bf16_f32 v5, v110, v111
	global_store_dword v[6:7], v5, off
	v_add_u32_e32 v6, 0x60, v4
	v_ashrrev_i32_e32 v7, 31, v6
	v_lshlrev_b64 v[6:7], 11, v[6:7]
	s_waitcnt lgkmcnt(1)
	v_cvt_pk_bf16_f32 v5, v112, v113
	v_lshl_add_u64 v[6:7], v[2:3], 0, v[6:7]
	v_add_u32_e32 v4, 0x70, v4
	global_store_dword v[6:7], v5, off
	v_ashrrev_i32_e32 v5, 31, v4
	v_lshlrev_b64 v[4:5], 11, v[4:5]
	v_lshl_add_u64 v[2:3], v[2:3], 0, v[4:5]
	v_readlane_b32 s41, v254, 51
	v_readlane_b32 s42, v254, 52
	v_readlane_b32 s43, v254, 53
	s_mov_b64 s[46:47], s[50:51]
	s_mov_b64 s[48:49], s[52:53]
	s_mov_b64 s[50:51], s[54:55]
	s_waitcnt lgkmcnt(0)
	v_cvt_pk_bf16_f32 v0, v114, v115
	global_store_dword v[2:3], v0, off
	s_barrier
	s_branch .LBB0_414

; __device__ __forceinline__ unsigned cvt_pk_bf16(float lo, float hi) { unsigned r; asm volatile("v_cvt_pk_bf16_f32 %0, %1, %2" : "=v"(r) : "v"(lo), "v"(hi)); return r; }
; __device__ void wt_tile(const float* src, int ld, int k0, int n0, bf16_t* dst, int Kdst, const float* kscale, float mul, LAS float* tile, bool rotperm = false, int drow0 = -1) {
;     ...
;     for (int i = 0; i < 16; ++i) { const int k = (tid >> 7) + 4 * i, n = tid & 127; v[i] = src[(size_t)(k0 + k) * ld + n0 + n]; }
; #pragma unroll
;     for (int i = 0; i < 16; ++i) { const int k = (tid >> 7) + 4 * i, n = tid & 127; float x = v[i] * mul; if (kscale) x *= kscale[k0 + k]; tile[k * 129 + n] = x; }
;     __syncthreads();
; #pragma unroll
;     for (int i = 0; i < 8; ++i) { const int n = (tid >> 5) + 16 * i, k2 = (tid & 31) * 2;
;         const float a = tile[k2 * 129 + n], b = tile[(k2 + 1) * 129 + n]; int nn = (drow0 >= 0 ? drow0 : n0) + n; if (rotperm) nn = (nn & ~127) | (2 * (nn & 63) + ((nn >> 6) & 1));
;         *(unsigned*)(dst + (size_t)nn * Kdst + k0 + k2) = cvt_pk_bf16(a, b); }
; __device__ void convert_rest(const Params& P, LAS float* tile, int sub, int nsub) {
;     ...
;     for (int t = sub; t < TT; t += nsub) {
;         if (t < T2) { const int kt = t & 15, ntl = t >> 4; wt_tile(P.in[12], DM, kt * 64, ntl * 128, (bf16_t*)(dob + DO_WOT), DM, nullptr, 1.0f, tile); }
;         else if (t < T2 + T3) { const int u = t - T2, kt = u & 15, ntl = u >> 4; wt_tile(P.in[14], DFF, kt * 64, ntl * 128, (bf16_t*)(dob + DO_WGT), DM, P.in[13], 1.0f, tile, false, ntl * 256); }
;         else if (t < T2 + T3 + T4) { const int u = t - T2 - T3, kt = u & 15, ntl = u >> 4; wt_tile(P.in[15], DFF, kt * 64, ntl * 128, (bf16_t*)(dob + DO_WGT), DM, P.in[13], 1.0f, tile, false, ntl * 256 + 128); }
;         else { const int u = t - T2 - T3 - T4, kt = u % 44, ntl = u / 44; wt_tile(P.in[18], DM, kt * 64, ntl * 128, (bf16_t*)(dob + DO_WDT), DFF, nullptr, 1.0f, tile); }
.LBB0_496:
	s_cmpk_gt_i32 s15, 0x7f
	s_mov_b64 s[4:5], -1
	s_cbranch_scc0 .LBB0_570
	s_cmpk_gt_u32 s15, 0x1df
	s_cbranch_scc0 .LBB0_535
	s_cmpk_gt_u32 s15, 0x33f
	s_cbranch_scc0 .LBB0_500
	s_add_i32 s5, s15, 0xfcc0
	s_and_b32 s4, s5, 0xffff
	s_mul_i32 s4, s4, 0xba2f
	s_lshr_b32 s4, s4, 21
	s_mul_i32 s16, s4, 44
	s_sub_i32 s5, s5, s16
	s_lshl_b32 s5, s5, 6
	v_mov_b32_e32 v6, v162
	v_readlane_b32 s40, v255, 2
	s_and_b32 s5, s5, 0xffc0
	s_lshl_b32 s16, s4, 9
	v_ashrrev_i32_e32 v7, 7, v6
	v_readlane_b32 s44, v255, 6
	v_add_u32_e32 v2, s5, v7
	v_readlane_b32 s45, v255, 7
	s_add_u32 s16, s44, s16
	v_lshlrev_b32_e32 v0, 2, v6
	s_addc_u32 s17, s45, 0
	v_and_b32_e32 v0, 0x1fc, v0
	v_ashrrev_i32_e32 v3, 31, v2
	v_lshl_add_u64 v[4:5], s[16:17], 0, v[0:1]
	v_lshlrev_b64 v[2:3], 12, v[2:3]
	v_lshl_add_u64 v[2:3], v[4:5], 0, v[2:3]
	s_movk_i32 s16, 0x4000
	v_add_co_u32_e32 v4, vcc, s16, v2
	s_mov_b32 s16, 0x8000
	s_nop 0
	v_addc_co_u32_e32 v5, vcc, 0, v3, vcc
	global_load_dword v8, v[2:3], off
	global_load_dword v9, v[4:5], off
	v_add_co_u32_e32 v4, vcc, s16, v2
	s_mov_b32 s16, 0xc000
	s_nop 0
	v_addc_co_u32_e32 v5, vcc, 0, v3, vcc
	global_load_dword v10, v[4:5], off
	v_add_co_u32_e32 v4, vcc, s16, v2
	s_mov_b32 s16, 0x10000
	s_nop 0
	v_addc_co_u32_e32 v5, vcc, 0, v3, vcc
	global_load_dword v11, v[4:5], off
	v_add_co_u32_e32 v4, vcc, s16, v2
	s_mov_b32 s16, 0x14000
	s_nop 0
	v_addc_co_u32_e32 v5, vcc, 0, v3, vcc
	global_load_dword v12, v[4:5], off
	v_add_co_u32_e32 v4, vcc, s16, v2
	s_mov_b32 s16, 0x18000
	s_nop 0
	v_addc_co_u32_e32 v5, vcc, 0, v3, vcc
	global_load_dword v13, v[4:5], off
	v_add_co_u32_e32 v4, vcc, s16, v2
	s_mov_b32 s16, 0x1c000
	s_nop 0
	v_addc_co_u32_e32 v5, vcc, 0, v3, vcc
	global_load_dword v14, v[4:5], off
	v_add_co_u32_e32 v4, vcc, s16, v2
	s_mov_b32 s16, 0x20000
	s_nop 0
	v_addc_co_u32_e32 v5, vcc, 0, v3, vcc
	global_load_dword v15, v[4:5], off
	v_add_co_u32_e32 v4, vcc, s16, v2
	s_mov_b32 s16, 0x24000
	s_nop 0
	v_addc_co_u32_e32 v5, vcc, 0, v3, vcc
	global_load_dword v16, v[4:5], off
	v_add_co_u32_e32 v4, vcc, s16, v2
	s_mov_b32 s16, 0x28000
	s_nop 0
	v_addc_co_u32_e32 v5, vcc, 0, v3, vcc
	global_load_dword v17, v[4:5], off
	v_add_co_u32_e32 v4, vcc, s16, v2
	s_mov_b32 s16, 0x2c000
	s_nop 0
	v_addc_co_u32_e32 v5, vcc, 0, v3, vcc
	global_load_dword v18, v[4:5], off
	v_add_co_u32_e32 v4, vcc, s16, v2
	s_mov_b32 s16, 0x30000
	s_nop 0
	v_addc_co_u32_e32 v5, vcc, 0, v3, vcc
	global_load_dword v19, v[4:5], off
	v_add_co_u32_e32 v4, vcc, s16, v2
	s_mov_b32 s16, 0x34000
	s_nop 0
	v_addc_co_u32_e32 v5, vcc, 0, v3, vcc
	global_load_dword v20, v[4:5], off
	v_add_co_u32_e32 v4, vcc, s16, v2
	s_mov_b32 s16, 0x38000
	s_nop 0
	v_addc_co_u32_e32 v5, vcc, 0, v3, vcc
	global_load_dword v21, v[4:5], off
	v_add_co_u32_e32 v4, vcc, s16, v2
	s_mov_b32 s16, 0x3c000
	s_nop 0
	v_addc_co_u32_e32 v5, vcc, 0, v3, vcc
	v_add_co_u32_e32 v2, vcc, s16, v2
	global_load_dword v4, v[4:5], off
	s_nop 0
	v_addc_co_u32_e32 v3, vcc, 0, v3, vcc
	global_load_dword v2, v[2:3], off
	s_movk_i32 s16, 0x204
	v_mul_lo_u32 v3, v7, s16
	v_add3_u32 v0, 0, v0, v3
	s_waitcnt vmcnt(0)
	ds_write_b32 v0, v8
	s_waitcnt vmcnt(14)
	ds_write_b32 v0, v9 offset:2064
	s_waitcnt vmcnt(13)
	ds_write_b32 v0, v10 offset:4128
	s_waitcnt vmcnt(12)
	ds_write_b32 v0, v11 offset:6192
	s_waitcnt vmcnt(11)
	ds_write_b32 v0, v12 offset:8256
	s_waitcnt vmcnt(10)
	ds_write_b32 v0, v13 offset:10320
	s_waitcnt vmcnt(9)
	ds_write_b32 v0, v14 offset:12384
	s_waitcnt vmcnt(8)
	ds_write_b32 v0, v15 offset:14448
	s_waitcnt vmcnt(7)
	ds_write_b32 v0, v16 offset:16512
	s_waitcnt vmcnt(6)
	ds_write_b32 v0, v17 offset:18576
	s_waitcnt vmcnt(5)
	ds_write_b32 v0, v18 offset:20640
	s_waitcnt vmcnt(4)
	ds_write_b32 v0, v19 offset:22704
	s_waitcnt vmcnt(3)
	ds_write_b32 v0, v20 offset:24768
	s_waitcnt vmcnt(2)
	ds_write_b32 v0, v21 offset:26832
	s_waitcnt vmcnt(1)
	ds_write_b32 v0, v4 offset:28896
	s_waitcnt vmcnt(0)
	ds_write_b32 v0, v2 offset:30960
	v_lshlrev_b32_e32 v0, 1, v6
	s_lshl_b32 s5, s5, 1
	v_and_b32_e32 v0, 62, v0
	s_add_u32 s16, s0, s5
	v_ashrrev_i32_e32 v4, 5, v6
	v_mul_u32_u24_e32 v5, 0x204, v0
	s_addc_u32 s17, s6, 0
	v_lshlrev_b32_e32 v0, 1, v0
	v_lshl_add_u64 v[2:3], s[16:17], 0, v[0:1]
	v_lshlrev_b32_e32 v0, 2, v4
	v_add3_u32 v0, 0, v5, v0
	s_waitcnt lgkmcnt(0)
	s_barrier
	ds_read2_b32 v[100:101], v0 offset1:129
	ds_read2_b32 v[102:103], v0 offset0:16 offset1:145
	ds_read2_b32 v[104:105], v0 offset0:32 offset1:161
	ds_read2_b32 v[106:107], v0 offset0:48 offset1:177
	ds_read2_b32 v[108:109], v0 offset0:64 offset1:193
	ds_read2_b32 v[110:111], v0 offset0:80 offset1:209
	ds_read2_b32 v[112:113], v0 offset0:96 offset1:225
	ds_read2_b32 v[114:115], v0 offset0:112 offset1:241
	v_lshl_add_u32 v6, s4, 7, v4
	s_movk_i32 s16, 0x1600
	s_waitcnt lgkmcnt(7)
	v_cvt_pk_bf16_f32 v7, v100, v101
	v_mad_i64_i32 v[4:5], s[4:5], v6, s16, v[2:3]
	global_store_dword v[4:5], v7, off
	v_add_u32_e32 v7, 16, v6
	s_waitcnt lgkmcnt(6)
	v_cvt_pk_bf16_f32 v8, v102, v103
	v_mad_i64_i32 v[4:5], s[4:5], v7, s16, v[2:3]
	global_store_dword v[4:5], v8, off
	v_add_u32_e32 v7, 32, v6
	s_waitcnt lgkmcnt(5)
	v_cvt_pk_bf16_f32 v8, v104, v105
	v_mad_i64_i32 v[4:5], s[4:5], v7, s16, v[2:3]
	global_store_dword v[4:5], v8, off
	v_add_u32_e32 v7, 48, v6
	s_waitcnt lgkmcnt(4)
	v_cvt_pk_bf16_f32 v8, v106, v107
	v_mad_i64_i32 v[4:5], s[4:5], v7, s16, v[2:3]
	global_store_dword v[4:5], v8, off
	v_add_u32_e32 v7, 64, v6
	s_waitcnt lgkmcnt(3)
	v_cvt_pk_bf16_f32 v8, v108, v109
	v_mad_i64_i32 v[4:5], s[4:5], v7, s16, v[2:3]
	global_store_dword v[4:5], v8, off
	v_add_u32_e32 v7, 0x50, v6
	s_waitcnt lgkmcnt(2)
	v_cvt_pk_bf16_f32 v8, v110, v111
	v_mad_i64_i32 v[4:5], s[4:5], v7, s16, v[2:3]
	global_store_dword v[4:5], v8, off
	v_add_u32_e32 v7, 0x60, v6
	v_add_u32_e32 v6, 0x70, v6
	s_waitcnt lgkmcnt(1)
	v_cvt_pk_bf16_f32 v8, v112, v113
	v_mad_i64_i32 v[4:5], s[4:5], v7, s16, v[2:3]
	v_mad_i64_i32 v[2:3], s[4:5], v6, s16, v[2:3]
	v_readlane_b32 s41, v255, 3
	v_readlane_b32 s42, v255, 4
	v_readlane_b32 s43, v255, 5
	v_readlane_b32 s46, v255, 8
	v_readlane_b32 s47, v255, 9
	v_readlane_b32 s48, v255, 10
	v_readlane_b32 s49, v255, 11
	v_readlane_b32 s50, v255, 12
	v_readlane_b32 s51, v255, 13
	v_readlane_b32 s52, v255, 14
	v_readlane_b32 s53, v255, 15
	v_readlane_b32 s54, v255, 16
	v_readlane_b32 s55, v255, 17
	global_store_dword v[4:5], v8, off
	s_waitcnt lgkmcnt(0)
	v_cvt_pk_bf16_f32 v0, v114, v115
	global_store_dword v[2:3], v0, off
	s_barrier
	s_mov_b64 s[4:5], 0

; __device__ __forceinline__ unsigned cvt_pk_bf16(float lo, float hi) { unsigned r; asm volatile("v_cvt_pk_bf16_f32 %0, %1, %2" : "=v"(r) : "v"(lo), "v"(hi)); return r; }
; __device__ void wt_tile(const float* src, int ld, int k0, int n0, bf16_t* dst, int Kdst, const float* kscale, float mul, LAS float* tile, bool rotperm = false, int drow0 = -1) {
;     ...
;     for (int i = 0; i < 16; ++i) { const int k = (tid >> 7) + 4 * i, n = tid & 127; v[i] = src[(size_t)(k0 + k) * ld + n0 + n]; }
; #pragma unroll
;     for (int i = 0; i < 16; ++i) { const int k = (tid >> 7) + 4 * i, n = tid & 127; float x = v[i] * mul; if (kscale) x *= kscale[k0 + k]; tile[k * 129 + n] = x; }
;     __syncthreads();
; #pragma unroll
;     for (int i = 0; i < 8; ++i) { const int n = (tid >> 5) + 16 * i, k2 = (tid & 31) * 2;
;         const float a = tile[k2 * 129 + n], b = tile[(k2 + 1) * 129 + n]; int nn = (drow0 >= 0 ? drow0 : n0) + n; if (rotperm) nn = (nn & ~127) | (2 * (nn & 63) + ((nn >> 6) & 1));
;         *(unsigned*)(dst + (size_t)nn * Kdst + k0 + k2) = cvt_pk_bf16(a, b); }
.LBB0_533:
	v_lshlrev_b32_e32 v0, 1, v4
	s_lshl_b32 s5, s5, 1
	v_and_b32_e32 v0, 62, v0
	s_add_u32 s16, s7, s5
	v_ashrrev_i32_e32 v5, 5, v4
	v_mul_u32_u24_e32 v4, 0x204, v0
	s_addc_u32 s17, s8, 0
	v_lshlrev_b32_e32 v0, 1, v0
	v_lshl_add_u64 v[2:3], s[16:17], 0, v[0:1]
	v_lshlrev_b32_e32 v0, 2, v5
	v_lshl_add_u32 v8, s4, 8, v5
	v_add3_u32 v0, 0, v4, v0
	v_add_u32_e32 v4, 0x80, v8
	v_ashrrev_i32_e32 v5, 31, v4
	v_lshlrev_b64 v[4:5], 11, v[4:5]
	s_waitcnt vmcnt(0)
	ds_write_b32 v11, v7 offset:30960
	s_waitcnt lgkmcnt(0)
	s_barrier
	ds_read2_b32 v[100:101], v0 offset1:129
	ds_read2_b32 v[102:103], v0 offset0:16 offset1:145
	ds_read2_b32 v[104:105], v0 offset0:32 offset1:161
	ds_read2_b32 v[106:107], v0 offset0:48 offset1:177
	ds_read2_b32 v[108:109], v0 offset0:64 offset1:193
	ds_read2_b32 v[110:111], v0 offset0:80 offset1:209
	ds_read2_b32 v[112:113], v0 offset0:96 offset1:225
	ds_read2_b32 v[114:115], v0 offset0:112 offset1:241
	v_lshl_add_u64 v[4:5], v[2:3], 0, v[4:5]
	s_waitcnt lgkmcnt(7)
	v_cvt_pk_bf16_f32 v6, v100, v101
	global_store_dword v[4:5], v6, off
	v_add_u32_e32 v4, 0x90, v8
	v_ashrrev_i32_e32 v5, 31, v4
	v_lshlrev_b64 v[4:5], 11, v[4:5]
	v_lshl_add_u64 v[4:5], v[2:3], 0, v[4:5]
	s_waitcnt lgkmcnt(6)
	v_cvt_pk_bf16_f32 v6, v102, v103
	global_store_dword v[4:5], v6, off
	v_add_u32_e32 v4, 0xa0, v8
	v_ashrrev_i32_e32 v5, 31, v4
	v_lshlrev_b64 v[4:5], 11, v[4:5]
	v_lshl_add_u64 v[4:5], v[2:3], 0, v[4:5]
	s_waitcnt lgkmcnt(5)
	v_cvt_pk_bf16_f32 v6, v104, v105
	global_store_dword v[4:5], v6, off
	v_add_u32_e32 v4, 0xb0, v8
	v_ashrrev_i32_e32 v5, 31, v4
	v_lshlrev_b64 v[4:5], 11, v[4:5]
	v_lshl_add_u64 v[4:5], v[2:3], 0, v[4:5]
	s_waitcnt lgkmcnt(4)
	v_cvt_pk_bf16_f32 v6, v106, v107
	global_store_dword v[4:5], v6, off
	v_add_u32_e32 v4, 0xc0, v8
	v_ashrrev_i32_e32 v5, 31, v4
	v_lshlrev_b64 v[4:5], 11, v[4:5]
	v_lshl_add_u64 v[4:5], v[2:3], 0, v[4:5]
	s_waitcnt lgkmcnt(3)
	v_cvt_pk_bf16_f32 v6, v108, v109
	global_store_dword v[4:5], v6, off
	v_add_u32_e32 v4, 0xd0, v8
	v_ashrrev_i32_e32 v5, 31, v4
	v_lshlrev_b64 v[4:5], 11, v[4:5]
	v_lshl_add_u64 v[4:5], v[2:3], 0, v[4:5]
	s_waitcnt lgkmcnt(2)
	v_cvt_pk_bf16_f32 v6, v110, v111
	global_store_dword v[4:5], v6, off
	v_add_u32_e32 v4, 0xe0, v8
	v_ashrrev_i32_e32 v5, 31, v4
	v_lshlrev_b64 v[4:5], 11, v[4:5]
	v_lshl_add_u64 v[4:5], v[2:3], 0, v[4:5]
	s_waitcnt lgkmcnt(1)
	v_cvt_pk_bf16_f32 v6, v112, v113
	global_store_dword v[4:5], v6, off
	v_add_u32_e32 v4, 0xf0, v8
	v_ashrrev_i32_e32 v5, 31, v4
	v_lshlrev_b64 v[4:5], 11, v[4:5]
	v_lshl_add_u64 v[2:3], v[2:3], 0, v[4:5]
	s_waitcnt lgkmcnt(0)
	v_cvt_pk_bf16_f32 v0, v114, v115
	global_store_dword v[2:3], v0, off
	s_barrier

; __device__ __forceinline__ unsigned cvt_pk_bf16(float lo, float hi) { unsigned r; asm volatile("v_cvt_pk_bf16_f32 %0, %1, %2" : "=v"(r) : "v"(lo), "v"(hi)); return r; }
; __device__ void wt_tile(const float* src, int ld, int k0, int n0, bf16_t* dst, int Kdst, const float* kscale, float mul, LAS float* tile, bool rotperm = false, int drow0 = -1) {
;     ...
;     for (int i = 0; i < 16; ++i) { const int k = (tid >> 7) + 4 * i, n = tid & 127; v[i] = src[(size_t)(k0 + k) * ld + n0 + n]; }
; #pragma unroll
;     for (int i = 0; i < 16; ++i) { const int k = (tid >> 7) + 4 * i, n = tid & 127; float x = v[i] * mul; if (kscale) x *= kscale[k0 + k]; tile[k * 129 + n] = x; }
;     __syncthreads();
; #pragma unroll
;     for (int i = 0; i < 8; ++i) { const int n = (tid >> 5) + 16 * i, k2 = (tid & 31) * 2;
;         const float a = tile[k2 * 129 + n], b = tile[(k2 + 1) * 129 + n]; int nn = (drow0 >= 0 ? drow0 : n0) + n; if (rotperm) nn = (nn & ~127) | (2 * (nn & 63) + ((nn >> 6) & 1));
;         *(unsigned*)(dst + (size_t)nn * Kdst + k0 + k2) = cvt_pk_bf16(a, b); }
.LBB0_568:
	v_lshlrev_b32_e32 v0, 1, v4
	s_lshl_b32 s5, s5, 1
	v_and_b32_e32 v0, 62, v0
	s_add_u32 s16, s7, s5
	v_ashrrev_i32_e32 v5, 5, v4
	v_mul_u32_u24_e32 v4, 0x204, v0
	s_addc_u32 s17, s8, 0
	v_lshlrev_b32_e32 v0, 1, v0
	v_lshl_add_u64 v[2:3], s[16:17], 0, v[0:1]
	v_lshlrev_b32_e32 v0, 2, v5
	v_add3_u32 v0, 0, v4, v0
	v_lshl_add_u32 v4, s4, 8, v5
	s_waitcnt vmcnt(0)
	ds_write_b32 v11, v7 offset:30960
	s_waitcnt lgkmcnt(0)
	s_barrier
	ds_read2_b32 v[100:101], v0 offset1:129
	ds_read2_b32 v[102:103], v0 offset0:16 offset1:145
	ds_read2_b32 v[104:105], v0 offset0:32 offset1:161
	ds_read2_b32 v[106:107], v0 offset0:48 offset1:177
	ds_read2_b32 v[108:109], v0 offset0:64 offset1:193
	ds_read2_b32 v[110:111], v0 offset0:80 offset1:209
	ds_read2_b32 v[112:113], v0 offset0:96 offset1:225
	ds_read2_b32 v[114:115], v0 offset0:112 offset1:241
	v_ashrrev_i32_e32 v5, 31, v4
	s_waitcnt lgkmcnt(7)
	v_cvt_pk_bf16_f32 v8, v100, v101
	v_lshlrev_b64 v[6:7], 11, v[4:5]
	v_lshl_add_u64 v[6:7], v[2:3], 0, v[6:7]
	global_store_dword v[6:7], v8, off
	v_add_u32_e32 v6, 16, v4
	v_ashrrev_i32_e32 v7, 31, v6
	v_lshlrev_b64 v[6:7], 11, v[6:7]
	v_lshl_add_u64 v[6:7], v[2:3], 0, v[6:7]
	s_waitcnt lgkmcnt(6)
	v_cvt_pk_bf16_f32 v5, v102, v103
	global_store_dword v[6:7], v5, off
	v_add_u32_e32 v6, 32, v4
	v_ashrrev_i32_e32 v7, 31, v6
	v_lshlrev_b64 v[6:7], 11, v[6:7]
	v_lshl_add_u64 v[6:7], v[2:3], 0, v[6:7]
	s_waitcnt lgkmcnt(5)
	v_cvt_pk_bf16_f32 v5, v104, v105
	global_store_dword v[6:7], v5, off
	v_add_u32_e32 v6, 48, v4
	v_ashrrev_i32_e32 v7, 31, v6
	v_lshlrev_b64 v[6:7], 11, v[6:7]
	v_lshl_add_u64 v[6:7], v[2:3], 0, v[6:7]
	s_waitcnt lgkmcnt(4)
	v_cvt_pk_bf16_f32 v5, v106, v107
	global_store_dword v[6:7], v5, off
	v_add_u32_e32 v6, 64, v4
	v_ashrrev_i32_e32 v7, 31, v6
	v_lshlrev_b64 v[6:7], 11, v[6:7]
	v_lshl_add_u64 v[6:7], v[2:3], 0, v[6:7]
	s_waitcnt lgkmcnt(3)
	v_cvt_pk_bf16_f32 v5, v108, v109
	global_store_dword v[6:7], v5, off
	v_add_u32_e32 v6, 0x50, v4
	v_ashrrev_i32_e32 v7, 31, v6
	v_lshlrev_b64 v[6:7], 11, v[6:7]
	v_lshl_add_u64 v[6:7], v[2:3], 0, v[6:7]
	s_waitcnt lgkmcnt(2)
	v_cvt_pk_bf16_f32 v5, v110, v111
	global_store_dword v[6:7], v5, off
	v_add_u32_e32 v6, 0x60, v4
	v_ashrrev_i32_e32 v7, 31, v6
	v_lshlrev_b64 v[6:7], 11, v[6:7]
	s_waitcnt lgkmcnt(1)
	v_cvt_pk_bf16_f32 v5, v112, v113
	v_lshl_add_u64 v[6:7], v[2:3], 0, v[6:7]
	v_add_u32_e32 v4, 0x70, v4
	global_store_dword v[6:7], v5, off
	v_ashrrev_i32_e32 v5, 31, v4
	v_lshlrev_b64 v[4:5], 11, v[4:5]
	v_lshl_add_u64 v[2:3], v[2:3], 0, v[4:5]
	s_waitcnt lgkmcnt(0)
	v_cvt_pk_bf16_f32 v0, v114, v115
	global_store_dword v[2:3], v0, off
	s_barrier

; __device__ __forceinline__ unsigned cvt_pk_bf16(float lo, float hi) { unsigned r; asm volatile("v_cvt_pk_bf16_f32 %0, %1, %2" : "=v"(r) : "v"(lo), "v"(hi)); return r; }
; __device__ void wt_tile(const float* src, int ld, int k0, int n0, bf16_t* dst, int Kdst, const float* kscale, float mul, LAS float* tile, bool rotperm = false, int drow0 = -1) {
;     ...
;     for (int i = 0; i < 16; ++i) { const int k = (tid >> 7) + 4 * i, n = tid & 127; v[i] = src[(size_t)(k0 + k) * ld + n0 + n]; }
; #pragma unroll
;     for (int i = 0; i < 16; ++i) { const int k = (tid >> 7) + 4 * i, n = tid & 127; float x = v[i] * mul; if (kscale) x *= kscale[k0 + k]; tile[k * 129 + n] = x; }
;     __syncthreads();
; #pragma unroll
;     for (int i = 0; i < 8; ++i) { const int n = (tid >> 5) + 16 * i, k2 = (tid & 31) * 2;
;         const float a = tile[k2 * 129 + n], b = tile[(k2 + 1) * 129 + n]; int nn = (drow0 >= 0 ? drow0 : n0) + n; if (rotperm) nn = (nn & ~127) | (2 * (nn & 63) + ((nn >> 6) & 1));
;         *(unsigned*)(dst + (size_t)nn * Kdst + k0 + k2) = cvt_pk_bf16(a, b); }
.LBB0_570:
	s_andn2_b64 vcc, exec, s[4:5]
	s_cbranch_vccnz .LBB0_495
	s_and_b32 s4, s13, 0xffffff80
	v_readlane_b32 s40, v254, 50
	v_mov_b32_e32 v6, v162
	s_ashr_i32 s5, s4, 31
	v_readlane_b32 s44, v254, 54
	v_readlane_b32 s45, v254, 55
	v_readlane_b32 s46, v254, 56
	v_readlane_b32 s47, v254, 57
	v_readlane_b32 s48, v254, 58
	v_readlane_b32 s49, v254, 59
	v_readlane_b32 s50, v254, 60
	v_readlane_b32 s51, v254, 61
	s_and_b32 s16, s11, 0x3c0
	s_lshl_b64 s[18:19], s[4:5], 2
	v_ashrrev_i32_e32 v7, 7, v6
	v_readlane_b32 s52, v254, 62
	v_readlane_b32 s53, v254, 63
	v_readlane_b32 s54, v255, 0
	v_readlane_b32 s55, v255, 1
	s_mov_b64 s[44:45], s[48:49]
	v_add_u32_e32 v2, s16, v7
	s_add_u32 s18, s44, s18
	v_lshlrev_b32_e32 v0, 2, v6
	s_addc_u32 s19, s45, s19
	v_and_b32_e32 v0, 0x1fc, v0
	v_ashrrev_i32_e32 v3, 31, v2
	v_lshl_add_u64 v[4:5], s[18:19], 0, v[0:1]
	v_lshlrev_b64 v[2:3], 12, v[2:3]
	v_lshl_add_u64 v[2:3], v[4:5], 0, v[2:3]
	s_movk_i32 s5, 0x4000
	v_add_co_u32_e32 v4, vcc, s5, v2
	s_mov_b32 s5, 0x8000
	s_nop 0
	v_addc_co_u32_e32 v5, vcc, 0, v3, vcc
	global_load_dword v8, v[2:3], off
	global_load_dword v9, v[4:5], off
	v_add_co_u32_e32 v4, vcc, s5, v2
	s_mov_b32 s5, 0xc000
	s_nop 0
	v_addc_co_u32_e32 v5, vcc, 0, v3, vcc
	global_load_dword v10, v[4:5], off
	v_add_co_u32_e32 v4, vcc, s5, v2
	s_mov_b32 s5, 0x10000
	s_nop 0
	v_addc_co_u32_e32 v5, vcc, 0, v3, vcc
	global_load_dword v11, v[4:5], off
	v_add_co_u32_e32 v4, vcc, s5, v2
	s_mov_b32 s5, 0x14000
	s_nop 0
	v_addc_co_u32_e32 v5, vcc, 0, v3, vcc
	global_load_dword v12, v[4:5], off
	v_add_co_u32_e32 v4, vcc, s5, v2
	s_mov_b32 s5, 0x18000
	s_nop 0
	v_addc_co_u32_e32 v5, vcc, 0, v3, vcc
	global_load_dword v13, v[4:5], off
	v_add_co_u32_e32 v4, vcc, s5, v2
	s_mov_b32 s5, 0x1c000
	s_nop 0
	v_addc_co_u32_e32 v5, vcc, 0, v3, vcc
	global_load_dword v14, v[4:5], off
	v_add_co_u32_e32 v4, vcc, s5, v2
	s_mov_b32 s5, 0x20000
	s_nop 0
	v_addc_co_u32_e32 v5, vcc, 0, v3, vcc
	global_load_dword v15, v[4:5], off
	v_add_co_u32_e32 v4, vcc, s5, v2
	s_mov_b32 s5, 0x24000
	s_nop 0
	v_addc_co_u32_e32 v5, vcc, 0, v3, vcc
	global_load_dword v16, v[4:5], off
	v_add_co_u32_e32 v4, vcc, s5, v2
	s_mov_b32 s5, 0x28000
	s_nop 0
	v_addc_co_u32_e32 v5, vcc, 0, v3, vcc
	global_load_dword v17, v[4:5], off
	v_add_co_u32_e32 v4, vcc, s5, v2
	s_mov_b32 s5, 0x2c000
	s_nop 0
	v_addc_co_u32_e32 v5, vcc, 0, v3, vcc
	global_load_dword v18, v[4:5], off
	v_add_co_u32_e32 v4, vcc, s5, v2
	s_mov_b32 s5, 0x30000
	s_nop 0
	v_addc_co_u32_e32 v5, vcc, 0, v3, vcc
	global_load_dword v19, v[4:5], off
	v_add_co_u32_e32 v4, vcc, s5, v2
	s_mov_b32 s5, 0x34000
	s_nop 0
	v_addc_co_u32_e32 v5, vcc, 0, v3, vcc
	global_load_dword v20, v[4:5], off
	v_add_co_u32_e32 v4, vcc, s5, v2
	s_mov_b32 s5, 0x38000
	s_nop 0
	v_addc_co_u32_e32 v5, vcc, 0, v3, vcc
	global_load_dword v21, v[4:5], off
	v_add_co_u32_e32 v4, vcc, s5, v2
	s_mov_b32 s5, 0x3c000
	s_nop 0
	v_addc_co_u32_e32 v5, vcc, 0, v3, vcc
	v_add_co_u32_e32 v2, vcc, s5, v2
	global_load_dword v4, v[4:5], off
	s_nop 0
	v_addc_co_u32_e32 v3, vcc, 0, v3, vcc
	global_load_dword v2, v[2:3], off
	s_movk_i32 s5, 0x204
	v_mul_lo_u32 v3, v7, s5
	v_add3_u32 v0, 0, v0, v3
	s_waitcnt vmcnt(0)
	ds_write_b32 v0, v8
	s_waitcnt vmcnt(14)
	ds_write_b32 v0, v9 offset:2064
	s_waitcnt vmcnt(13)
	ds_write_b32 v0, v10 offset:4128
	s_waitcnt vmcnt(12)
	ds_write_b32 v0, v11 offset:6192
	s_waitcnt vmcnt(11)
	ds_write_b32 v0, v12 offset:8256
	s_waitcnt vmcnt(10)
	ds_write_b32 v0, v13 offset:10320
	s_waitcnt vmcnt(9)
	ds_write_b32 v0, v14 offset:12384
	s_waitcnt vmcnt(8)
	ds_write_b32 v0, v15 offset:14448
	s_waitcnt vmcnt(7)
	ds_write_b32 v0, v16 offset:16512
	s_waitcnt vmcnt(6)
	ds_write_b32 v0, v17 offset:18576
	s_waitcnt vmcnt(5)
	ds_write_b32 v0, v18 offset:20640
	s_waitcnt vmcnt(4)
	ds_write_b32 v0, v19 offset:22704
	s_waitcnt vmcnt(3)
	ds_write_b32 v0, v20 offset:24768
	s_waitcnt vmcnt(2)
	ds_write_b32 v0, v21 offset:26832
	s_waitcnt vmcnt(1)
	ds_write_b32 v0, v4 offset:28896
	s_waitcnt vmcnt(0)
	ds_write_b32 v0, v2 offset:30960
	v_lshlrev_b32_e32 v0, 1, v6
	s_lshl_b32 s5, s16, 1
	v_and_b32_e32 v0, 62, v0
	s_add_u32 s16, s9, s5
	v_ashrrev_i32_e32 v4, 5, v6
	v_mul_u32_u24_e32 v5, 0x204, v0
	s_addc_u32 s17, s10, 0
	v_lshlrev_b32_e32 v0, 1, v0
	v_lshl_add_u64 v[2:3], s[16:17], 0, v[0:1]
	v_lshlrev_b32_e32 v0, 2, v4
	v_add3_u32 v0, 0, v5, v0
	v_add_u32_e32 v4, s4, v4
	s_waitcnt lgkmcnt(0)
	s_barrier
	ds_read2_b32 v[100:101], v0 offset1:129
	ds_read2_b32 v[102:103], v0 offset0:16 offset1:145
	ds_read2_b32 v[104:105], v0 offset0:32 offset1:161
	ds_read2_b32 v[106:107], v0 offset0:48 offset1:177
	ds_read2_b32 v[108:109], v0 offset0:64 offset1:193
	ds_read2_b32 v[110:111], v0 offset0:80 offset1:209
	ds_read2_b32 v[112:113], v0 offset0:96 offset1:225
	ds_read2_b32 v[114:115], v0 offset0:112 offset1:241
	v_ashrrev_i32_e32 v5, 31, v4
	s_waitcnt lgkmcnt(7)
	v_cvt_pk_bf16_f32 v8, v100, v101
	v_lshlrev_b64 v[6:7], 11, v[4:5]
	v_lshl_add_u64 v[6:7], v[2:3], 0, v[6:7]
	global_store_dword v[6:7], v8, off
	v_add_u32_e32 v6, 16, v4
	v_ashrrev_i32_e32 v7, 31, v6
	v_lshlrev_b64 v[6:7], 11, v[6:7]
	v_lshl_add_u64 v[6:7], v[2:3], 0, v[6:7]
	s_waitcnt lgkmcnt(6)
	v_cvt_pk_bf16_f32 v5, v102, v103
	global_store_dword v[6:7], v5, off
	v_add_u32_e32 v6, 32, v4
	v_ashrrev_i32_e32 v7, 31, v6
	v_lshlrev_b64 v[6:7], 11, v[6:7]
	v_lshl_add_u64 v[6:7], v[2:3], 0, v[6:7]
	s_waitcnt lgkmcnt(5)
	v_cvt_pk_bf16_f32 v5, v104, v105
	global_store_dword v[6:7], v5, off
	v_add_u32_e32 v6, 48, v4
	v_ashrrev_i32_e32 v7, 31, v6
	v_lshlrev_b64 v[6:7], 11, v[6:7]
	v_lshl_add_u64 v[6:7], v[2:3], 0, v[6:7]
	s_waitcnt lgkmcnt(4)
	v_cvt_pk_bf16_f32 v5, v106, v107
	global_store_dword v[6:7], v5, off
	v_add_u32_e32 v6, 64, v4
	v_ashrrev_i32_e32 v7, 31, v6
	v_lshlrev_b64 v[6:7], 11, v[6:7]
	v_lshl_add_u64 v[6:7], v[2:3], 0, v[6:7]
	s_waitcnt lgkmcnt(3)
	v_cvt_pk_bf16_f32 v5, v108, v109
	global_store_dword v[6:7], v5, off
	v_add_u32_e32 v6, 0x50, v4
	v_ashrrev_i32_e32 v7, 31, v6
	v_lshlrev_b64 v[6:7], 11, v[6:7]
	v_lshl_add_u64 v[6:7], v[2:3], 0, v[6:7]
	s_waitcnt lgkmcnt(2)
	v_cvt_pk_bf16_f32 v5, v110, v111
	global_store_dword v[6:7], v5, off
	v_add_u32_e32 v6, 0x60, v4
	v_ashrrev_i32_e32 v7, 31, v6
	v_lshlrev_b64 v[6:7], 11, v[6:7]
	s_waitcnt lgkmcnt(1)
	v_cvt_pk_bf16_f32 v5, v112, v113
	v_lshl_add_u64 v[6:7], v[2:3], 0, v[6:7]
	v_add_u32_e32 v4, 0x70, v4
	global_store_dword v[6:7], v5, off
	v_ashrrev_i32_e32 v5, 31, v4
	v_lshlrev_b64 v[4:5], 11, v[4:5]
	v_lshl_add_u64 v[2:3], v[2:3], 0, v[4:5]
	v_readlane_b32 s41, v254, 51
	v_readlane_b32 s42, v254, 52
	v_readlane_b32 s43, v254, 53
	s_mov_b64 s[46:47], s[50:51]
	s_mov_b64 s[48:49], s[52:53]
	s_mov_b64 s[50:51], s[54:55]
	s_waitcnt lgkmcnt(0)
	v_cvt_pk_bf16_f32 v0, v114, v115
	global_store_dword v[2:3], v0, off
	s_barrier
	s_branch .LBB0_495

; __device__ __forceinline__ unsigned cvt_pk_bf16(float lo, float hi) { unsigned r; asm volatile("v_cvt_pk_bf16_f32 %0, %1, %2" : "=v"(r) : "v"(lo), "v"(hi)); return r; }
; __device__ void wt_tile(const float* src, int ld, int k0, int n0, bf16_t* dst, int Kdst, const float* kscale, float mul, LAS float* tile, bool rotperm = false, int drow0 = -1) {
;     ...
;     for (int i = 0; i < 16; ++i) { const int k = (tid >> 7) + 4 * i, n = tid & 127; v[i] = src[(size_t)(k0 + k) * ld + n0 + n]; }
; #pragma unroll
;     for (int i = 0; i < 16; ++i) { const int k = (tid >> 7) + 4 * i, n = tid & 127; float x = v[i] * mul; if (kscale) x *= kscale[k0 + k]; tile[k * 129 + n] = x; }
;     __syncthreads();
; #pragma unroll
;     for (int i = 0; i < 8; ++i) { const int n = (tid >> 5) + 16 * i, k2 = (tid & 31) * 2;
;         const float a = tile[k2 * 129 + n], b = tile[(k2 + 1) * 129 + n]; int nn = (drow0 >= 0 ? drow0 : n0) + n; if (rotperm) nn = (nn & ~127) | (2 * (nn & 63) + ((nn >> 6) & 1));
;         *(unsigned*)(dst + (size_t)nn * Kdst + k0 + k2) = cvt_pk_bf16(a, b); }
.LBB0_985:
	v_lshlrev_b32_e32 v0, 1, v4
	s_lshl_b32 s5, s17, 1
	v_and_b32_e32 v0, 62, v0
	s_add_u32 s18, s9, s5
	ds_write_b32 v5, v18 offset:30960
	v_ashrrev_i32_e32 v5, 5, v4
	v_mul_u32_u24_e32 v4, 0x204, v0
	s_addc_u32 s19, s10, 0
	v_lshlrev_b32_e32 v0, 1, v0
	v_lshl_add_u64 v[2:3], s[18:19], 0, v[0:1]
	v_lshlrev_b32_e32 v0, 2, v5
	v_add3_u32 v0, 0, v4, v0
	v_add_u32_e32 v4, s4, v5
	s_waitcnt lgkmcnt(0)
	s_barrier
	ds_read2_b32 v[66:67], v0 offset1:129
	ds_read2_b32 v[68:69], v0 offset0:16 offset1:145
	ds_read2_b32 v[70:71], v0 offset0:32 offset1:161
	ds_read2_b32 v[72:73], v0 offset0:48 offset1:177
	ds_read2_b32 v[74:75], v0 offset0:64 offset1:193
	ds_read2_b32 v[76:77], v0 offset0:80 offset1:209
	ds_read2_b32 v[78:79], v0 offset0:96 offset1:225
	ds_read2_b32 v[80:81], v0 offset0:112 offset1:241
	v_ashrrev_i32_e32 v5, 31, v4
	s_waitcnt lgkmcnt(7)
	v_cvt_pk_bf16_f32 v8, v66, v67
	v_lshlrev_b64 v[6:7], 11, v[4:5]
	v_lshl_add_u64 v[6:7], v[2:3], 0, v[6:7]
	global_store_dword v[6:7], v8, off
	v_add_u32_e32 v6, 16, v4
	v_ashrrev_i32_e32 v7, 31, v6
	v_lshlrev_b64 v[6:7], 11, v[6:7]
	v_lshl_add_u64 v[6:7], v[2:3], 0, v[6:7]
	s_waitcnt lgkmcnt(6)
	v_cvt_pk_bf16_f32 v5, v68, v69
	global_store_dword v[6:7], v5, off
	v_add_u32_e32 v6, 32, v4
	v_ashrrev_i32_e32 v7, 31, v6
	v_lshlrev_b64 v[6:7], 11, v[6:7]
	v_lshl_add_u64 v[6:7], v[2:3], 0, v[6:7]
	s_waitcnt lgkmcnt(5)
	v_cvt_pk_bf16_f32 v5, v70, v71
	global_store_dword v[6:7], v5, off
	v_add_u32_e32 v6, 48, v4
	v_ashrrev_i32_e32 v7, 31, v6
	v_lshlrev_b64 v[6:7], 11, v[6:7]
	v_lshl_add_u64 v[6:7], v[2:3], 0, v[6:7]
	s_waitcnt lgkmcnt(4)
	v_cvt_pk_bf16_f32 v5, v72, v73
	global_store_dword v[6:7], v5, off
	v_add_u32_e32 v6, 64, v4
	v_ashrrev_i32_e32 v7, 31, v6
	v_lshlrev_b64 v[6:7], 11, v[6:7]
	v_lshl_add_u64 v[6:7], v[2:3], 0, v[6:7]
	s_waitcnt lgkmcnt(3)
	v_cvt_pk_bf16_f32 v5, v74, v75
	global_store_dword v[6:7], v5, off
	v_add_u32_e32 v6, 0x50, v4
	v_ashrrev_i32_e32 v7, 31, v6
	v_lshlrev_b64 v[6:7], 11, v[6:7]
	v_lshl_add_u64 v[6:7], v[2:3], 0, v[6:7]
	s_waitcnt lgkmcnt(2)
	v_cvt_pk_bf16_f32 v5, v76, v77
	global_store_dword v[6:7], v5, off
	v_add_u32_e32 v6, 0x60, v4
	v_ashrrev_i32_e32 v7, 31, v6
	v_lshlrev_b64 v[6:7], 11, v[6:7]
	s_waitcnt lgkmcnt(1)
	v_cvt_pk_bf16_f32 v5, v78, v79
	v_lshl_add_u64 v[6:7], v[2:3], 0, v[6:7]
	v_add_u32_e32 v4, 0x70, v4
	global_store_dword v[6:7], v5, off
	v_ashrrev_i32_e32 v5, 31, v4
	v_lshlrev_b64 v[4:5], 11, v[4:5]
	v_lshl_add_u64 v[2:3], v[2:3], 0, v[4:5]
	s_waitcnt lgkmcnt(0)
	v_cvt_pk_bf16_f32 v0, v80, v81
	global_store_dword v[2:3], v0, off
	s_barrier

; __device__ __forceinline__ unsigned cvt_pk_bf16(float lo, float hi) { unsigned r; asm volatile("v_cvt_pk_bf16_f32 %0, %1, %2" : "=v"(r) : "v"(lo), "v"(hi)); return r; }
; __device__ void wt_tile(const float* src, int ld, int k0, int n0, bf16_t* dst, int Kdst, const float* kscale, float mul, LAS float* tile, bool rotperm = false, int drow0 = -1) {
;     ...
;     for (int i = 0; i < 16; ++i) { const int k = (tid >> 7) + 4 * i, n = tid & 127; v[i] = src[(size_t)(k0 + k) * ld + n0 + n]; }
; #pragma unroll
;     for (int i = 0; i < 16; ++i) { const int k = (tid >> 7) + 4 * i, n = tid & 127; float x = v[i] * mul; if (kscale) x *= kscale[k0 + k]; tile[k * 129 + n] = x; }
;     __syncthreads();
; #pragma unroll
;     for (int i = 0; i < 8; ++i) { const int n = (tid >> 5) + 16 * i, k2 = (tid & 31) * 2;
;         const float a = tile[k2 * 129 + n], b = tile[(k2 + 1) * 129 + n]; int nn = (drow0 >= 0 ? drow0 : n0) + n; if (rotperm) nn = (nn & ~127) | (2 * (nn & 63) + ((nn >> 6) & 1));
;         *(unsigned*)(dst + (size_t)nn * Kdst + k0 + k2) = cvt_pk_bf16(a, b); }
; __global__ void __launch_bounds__(512, 2) mega(Params P0) {
;     ...
;                         for (int t = sub; t < 128 + 32; t += nfree) {
;                             if (t < 128) { const int kt = t & 15, ntl = t >> 4; wt_tile(P.in[21], DM, kt * 64, ntl * 128, (bf16_t*)(ws + WS_WPG), DM, P.in[20], 1.0f, tile); }
;                             else { const int u2 = t - 128, kt = u2 & 3, ntl = u2 >> 2; wt_tile(P.in[19], DM, kt * 64, ntl * 128, (bf16_t*)(ws + WS_WPP), PLE, nullptr, 1.0f, tile); } } } } }
.LBB0_987:
	s_cmpk_gt_i32 s0, 0x7f
	s_mov_b64 s[4:5], -1
	s_movk_i32 s22, 0x204
	s_cbranch_scc0 .LBB0_989
	s_and_b32 s5, s11, 0x7fffff80
	v_readlane_b32 s40, v255, 2
	s_add_i32 s38, s5, 0xfffff000
	v_mov_b32_e32 v6, v162
	v_readlane_b32 s42, v255, 4
	v_readlane_b32 s43, v255, 5
	v_readlane_b32 s46, v255, 8
	v_readlane_b32 s47, v255, 9
	s_and_b32 s4, s13, 0xc0
	s_lshl_b64 s[18:19], s[38:39], 2
	v_ashrrev_i32_e32 v7, 7, v6
	s_mov_b64 s[42:43], s[46:47]
	v_add_u32_e32 v2, s4, v7
	s_add_u32 s18, s42, s18
	v_lshlrev_b32_e32 v0, 2, v6
	s_addc_u32 s19, s43, s19
	v_and_b32_e32 v0, 0x1fc, v0
	s_waitcnt lgkmcnt(0)
	v_ashrrev_i32_e32 v3, 31, v2
	v_lshl_add_u64 v[4:5], s[18:19], 0, v[0:1]
	v_lshlrev_b64 v[2:3], 12, v[2:3]
	v_lshl_add_u64 v[2:3], v[4:5], 0, v[2:3]
	v_add_co_u32_e32 v4, vcc, s24, v2
	s_mov_b32 s5, 0x8000
	s_nop 0
	v_addc_co_u32_e32 v5, vcc, 0, v3, vcc
	global_load_dword v8, v[2:3], off
	global_load_dword v9, v[4:5], off
	v_add_co_u32_e32 v4, vcc, s5, v2
	s_mov_b32 s5, 0xc000
	s_nop 0
	v_addc_co_u32_e32 v5, vcc, 0, v3, vcc
	global_load_dword v10, v[4:5], off
	v_add_co_u32_e32 v4, vcc, s5, v2
	s_mov_b32 s5, 0x10000
	s_nop 0
	v_addc_co_u32_e32 v5, vcc, 0, v3, vcc
	global_load_dword v11, v[4:5], off
	v_add_co_u32_e32 v4, vcc, s5, v2
	s_mov_b32 s5, 0x14000
	s_nop 0
	v_addc_co_u32_e32 v5, vcc, 0, v3, vcc
	global_load_dword v12, v[4:5], off
	v_add_co_u32_e32 v4, vcc, s5, v2
	s_mov_b32 s5, 0x18000
	s_nop 0
	v_addc_co_u32_e32 v5, vcc, 0, v3, vcc
	global_load_dword v13, v[4:5], off
	v_add_co_u32_e32 v4, vcc, s5, v2
	s_mov_b32 s5, 0x1c000
	s_nop 0
	v_addc_co_u32_e32 v5, vcc, 0, v3, vcc
	global_load_dword v14, v[4:5], off
	v_add_co_u32_e32 v4, vcc, s5, v2
	s_mov_b32 s5, 0x20000
	s_nop 0
	v_addc_co_u32_e32 v5, vcc, 0, v3, vcc
	global_load_dword v15, v[4:5], off
	v_add_co_u32_e32 v4, vcc, s5, v2
	s_mov_b32 s5, 0x24000
	s_nop 0
	v_addc_co_u32_e32 v5, vcc, 0, v3, vcc
	global_load_dword v16, v[4:5], off
	v_add_co_u32_e32 v4, vcc, s5, v2
	s_mov_b32 s5, 0x28000
	s_nop 0
	v_addc_co_u32_e32 v5, vcc, 0, v3, vcc
	global_load_dword v17, v[4:5], off
	v_add_co_u32_e32 v4, vcc, s5, v2
	s_mov_b32 s5, 0x2c000
	s_nop 0
	v_addc_co_u32_e32 v5, vcc, 0, v3, vcc
	global_load_dword v18, v[4:5], off
	v_add_co_u32_e32 v4, vcc, s5, v2
	s_mov_b32 s5, 0x30000
	s_nop 0
	v_addc_co_u32_e32 v5, vcc, 0, v3, vcc
	global_load_dword v19, v[4:5], off
	v_add_co_u32_e32 v4, vcc, s5, v2
	s_mov_b32 s5, 0x34000
	s_nop 0
	v_addc_co_u32_e32 v5, vcc, 0, v3, vcc
	global_load_dword v20, v[4:5], off
	v_add_co_u32_e32 v4, vcc, s5, v2
	s_mov_b32 s5, 0x38000
	s_nop 0
	v_addc_co_u32_e32 v5, vcc, 0, v3, vcc
	global_load_dword v21, v[4:5], off
	v_add_co_u32_e32 v4, vcc, s5, v2
	s_mov_b32 s5, 0x3c000
	s_nop 0
	v_addc_co_u32_e32 v5, vcc, 0, v3, vcc
	v_add_co_u32_e32 v2, vcc, s5, v2
	global_load_dword v4, v[4:5], off
	s_nop 0
	v_addc_co_u32_e32 v3, vcc, 0, v3, vcc
	global_load_dword v2, v[2:3], off
	v_mul_lo_u32 v3, v7, s22
	v_add3_u32 v0, 0, v0, v3
	s_waitcnt vmcnt(0)
	ds_write_b32 v0, v8
	ds_write_b32 v0, v9 offset:2064
	ds_write_b32 v0, v10 offset:4128
	ds_write_b32 v0, v11 offset:6192
	ds_write_b32 v0, v12 offset:8256
	ds_write_b32 v0, v13 offset:10320
	ds_write_b32 v0, v14 offset:12384
	ds_write_b32 v0, v15 offset:14448
	ds_write_b32 v0, v16 offset:16512
	ds_write_b32 v0, v17 offset:18576
	ds_write_b32 v0, v18 offset:20640
	ds_write_b32 v0, v19 offset:22704
	ds_write_b32 v0, v20 offset:24768
	ds_write_b32 v0, v21 offset:26832
	ds_write_b32 v0, v4 offset:28896
	ds_write_b32 v0, v2 offset:30960
	v_lshlrev_b32_e32 v0, 1, v6
	s_lshl_b32 s4, s4, 1
	v_and_b32_e32 v0, 62, v0
	s_add_u32 s4, s6, s4
	v_ashrrev_i32_e32 v4, 5, v6
	v_mul_u32_u24_e32 v5, 0x204, v0
	s_addc_u32 s5, s7, 0
	v_lshlrev_b32_e32 v0, 1, v0
	v_lshl_add_u64 v[2:3], s[4:5], 0, v[0:1]
	v_lshlrev_b32_e32 v0, 2, v4
	v_add3_u32 v0, 0, v5, v0
	v_add_u32_e32 v4, s38, v4
	s_waitcnt lgkmcnt(0)
	s_barrier
	ds_read2_b32 v[40:41], v0 offset1:129
	ds_read2_b32 v[42:43], v0 offset0:16 offset1:145
	ds_read2_b32 v[44:45], v0 offset0:32 offset1:161
	ds_read2_b32 v[46:47], v0 offset0:48 offset1:177
	ds_read2_b32 v[48:49], v0 offset0:64 offset1:193
	ds_read2_b32 v[50:51], v0 offset0:80 offset1:209
	ds_read2_b32 v[52:53], v0 offset0:96 offset1:225
	ds_read2_b32 v[54:55], v0 offset0:112 offset1:241
	v_ashrrev_i32_e32 v5, 31, v4
	s_waitcnt lgkmcnt(7)
	v_cvt_pk_bf16_f32 v8, v40, v41
	v_lshlrev_b64 v[6:7], 9, v[4:5]
	v_lshl_add_u64 v[6:7], v[2:3], 0, v[6:7]
	global_store_dword v[6:7], v8, off
	v_add_u32_e32 v6, 16, v4
	v_ashrrev_i32_e32 v7, 31, v6
	v_lshlrev_b64 v[6:7], 9, v[6:7]
	v_lshl_add_u64 v[6:7], v[2:3], 0, v[6:7]
	s_waitcnt lgkmcnt(6)
	v_cvt_pk_bf16_f32 v5, v42, v43
	global_store_dword v[6:7], v5, off
	v_add_u32_e32 v6, 32, v4
	v_ashrrev_i32_e32 v7, 31, v6
	v_lshlrev_b64 v[6:7], 9, v[6:7]
	v_lshl_add_u64 v[6:7], v[2:3], 0, v[6:7]
	s_waitcnt lgkmcnt(5)
	v_cvt_pk_bf16_f32 v5, v44, v45
	global_store_dword v[6:7], v5, off
	v_add_u32_e32 v6, 48, v4
	v_ashrrev_i32_e32 v7, 31, v6
	v_lshlrev_b64 v[6:7], 9, v[6:7]
	v_lshl_add_u64 v[6:7], v[2:3], 0, v[6:7]
	s_waitcnt lgkmcnt(4)
	v_cvt_pk_bf16_f32 v5, v46, v47
	global_store_dword v[6:7], v5, off
	v_add_u32_e32 v6, 64, v4
	v_ashrrev_i32_e32 v7, 31, v6
	v_lshlrev_b64 v[6:7], 9, v[6:7]
	v_lshl_add_u64 v[6:7], v[2:3], 0, v[6:7]
	s_waitcnt lgkmcnt(3)
	v_cvt_pk_bf16_f32 v5, v48, v49
	global_store_dword v[6:7], v5, off
	v_add_u32_e32 v6, 0x50, v4
	v_ashrrev_i32_e32 v7, 31, v6
	v_lshlrev_b64 v[6:7], 9, v[6:7]
	v_lshl_add_u64 v[6:7], v[2:3], 0, v[6:7]
	s_waitcnt lgkmcnt(2)
	v_cvt_pk_bf16_f32 v5, v50, v51
	global_store_dword v[6:7], v5, off
	v_add_u32_e32 v6, 0x60, v4
	v_ashrrev_i32_e32 v7, 31, v6
	v_lshlrev_b64 v[6:7], 9, v[6:7]
	s_waitcnt lgkmcnt(1)
	v_cvt_pk_bf16_f32 v5, v52, v53
	v_lshl_add_u64 v[6:7], v[2:3], 0, v[6:7]
	v_add_u32_e32 v4, 0x70, v4
	global_store_dword v[6:7], v5, off
	v_ashrrev_i32_e32 v5, 31, v4
	v_lshlrev_b64 v[4:5], 9, v[4:5]
	v_lshl_add_u64 v[2:3], v[2:3], 0, v[4:5]
	v_readlane_b32 s41, v255, 3
	v_readlane_b32 s44, v255, 6
	v_readlane_b32 s45, v255, 7
	v_readlane_b32 s48, v255, 10
	v_readlane_b32 s49, v255, 11
	v_readlane_b32 s50, v255, 12
	v_readlane_b32 s51, v255, 13
	v_readlane_b32 s52, v255, 14
	v_readlane_b32 s53, v255, 15
	v_readlane_b32 s54, v255, 16
	v_readlane_b32 s55, v255, 17
	s_waitcnt lgkmcnt(0)
	v_cvt_pk_bf16_f32 v0, v54, v55
	global_store_dword v[2:3], v0, off
	s_barrier
	s_mov_b64 s[4:5], 0

; __device__ void wt_tile(const float* src, int ld, int k0, int n0, bf16_t* dst, int Kdst, const float* kscale, float mul, LAS float* tile, bool rotperm = false, int drow0 = -1) {
;     ...
;     for (int i = 0; i < 16; ++i) { const int k = (tid >> 7) + 4 * i, n = tid & 127; v[i] = src[(size_t)(k0 + k) * ld + n0 + n]; }
; #pragma unroll
;     for (int i = 0; i < 16; ++i) { const int k = (tid >> 7) + 4 * i, n = tid & 127; float x = v[i] * mul; if (kscale) x *= kscale[k0 + k]; tile[k * 129 + n] = x; }
;     __syncthreads();
.LBB0_1041:
	s_ashr_i32 s3, s7, 4
	s_and_b32 s8, s5, 0x3c0
	s_lshl_b32 s2, s3, 7
	v_mov_b32_e32 v0, v162
	s_cmp_lt_i32 s3, 4
	s_cselect_b64 vcc, -1, 0
	s_waitcnt lgkmcnt(0)
	v_lshlrev_b32_e32 v3, 2, v0
	v_ashrrev_i32_e32 v4, 5, v0
	v_lshlrev_b32_e32 v5, 1, v0
	s_cmp_lt_i32 s3, 8
	v_ashrrev_i32_e32 v2, 7, v0
	v_cndmask_b32_e32 v19, 1.0, v218, vcc
	v_and_b32_e32 v0, 0x1fc, v3
	s_waitcnt vmcnt(0)
	v_and_b32_e32 v44, 62, v5
	v_lshlrev_b32_e32 v3, 2, v4
	v_add_u32_e32 v5, s2, v4
	v_lshlrev_b32_e32 v6, 1, v4
	v_bfe_u32 v8, v4, 6, 1
	v_add_u32_e32 v9, 16, v4
	v_add_u32_e32 v10, 32, v4
	v_add_u32_e32 v11, 48, v4
	v_add_u32_e32 v12, 64, v4
	v_add_u32_e32 v13, 0x50, v4
	v_add_u32_e32 v14, 0x60, v4
	v_add_u32_e32 v4, 0x70, v4
	s_cselect_b64 vcc, -1, 0
	s_ashr_i32 s3, s2, 31
	v_add_u32_e32 v7, s8, v2
	v_mul_lo_u32 v2, v2, s9
	v_add_u32_e32 v21, s2, v9
	v_add_u32_e32 v25, s2, v10
	v_add_u32_e32 v29, s2, v11
	v_add_u32_e32 v47, s2, v12
	v_add_u32_e32 v48, s2, v13
	v_add_u32_e32 v49, s2, v14
	v_add_u32_e32 v50, s2, v4
	s_lshl_b64 s[2:3], s[2:3], 2
	v_add3_u32 v46, 0, v0, v2
	v_mul_u32_u24_e32 v2, 0x204, v44
	v_and_b32_e32 v17, 0xffffff80, v5
	v_and_b32_e32 v6, 0x7e, v6
	v_lshlrev_b32_e32 v23, 1, v9
	v_lshlrev_b32_e32 v27, 1, v10
	v_lshlrev_b32_e32 v31, 1, v11
	s_add_u32 s2, s14, s2
	v_bfe_u32 v9, v9, 6, 1
	v_bfe_u32 v10, v10, 6, 1
	v_bfe_u32 v11, v11, 6, 1
	v_lshlrev_b32_e32 v33, 1, v12
	v_lshlrev_b32_e32 v35, 1, v13
	v_or3_b32 v6, v8, v17, v6
	v_add3_u32 v51, 0, v2, v3
	v_and_b32_e32 v3, 0xffffff80, v21
	v_and_b32_e32 v8, 0x7e, v23
	v_and_b32_e32 v17, 0xffffff80, v25
	v_and_b32_e32 v23, 0x7e, v27
	v_and_b32_e32 v27, 0xffffff80, v29
	v_and_b32_e32 v31, 0x7e, v31
	s_addc_u32 s3, s15, s3
	v_add_u32_e32 v22, 16, v7
	v_add_u32_e32 v24, 20, v7
	v_add_u32_e32 v26, 24, v7
	v_add_u32_e32 v28, 28, v7
	v_add_u32_e32 v30, 32, v7
	v_add_u32_e32 v32, 36, v7
	v_bfe_u32 v12, v12, 6, 1
	v_bfe_u32 v13, v13, 6, 1
	v_lshlrev_b32_e32 v37, 1, v14
	v_lshlrev_b32_e32 v39, 1, v4
	v_and_b32_e32 v41, 0xffffff80, v47
	v_and_b32_e32 v33, 0x7e, v33
	v_and_b32_e32 v43, 0xffffff80, v48
	v_and_b32_e32 v35, 0x7e, v35
	v_cndmask_b32_e32 v2, v5, v6, vcc
	v_or3_b32 v5, v9, v3, v8
	v_or3_b32 v6, v10, v17, v23
	v_or3_b32 v8, v11, v27, v31
	v_lshl_add_u64 v[10:11], s[2:3], 0, v[0:1]
	v_add_u32_e32 v15, 4, v7
	v_add_u32_e32 v16, 8, v7
	v_add_u32_e32 v20, 12, v7
	v_add_u32_e32 v34, 40, v7
	v_add_u32_e32 v36, 44, v7
	v_add_u32_e32 v38, 48, v7
	v_add_u32_e32 v40, 52, v7
	v_add_u32_e32 v42, 56, v7
	v_add_u32_e32 v45, 60, v7
	v_bfe_u32 v14, v14, 6, 1
	v_bfe_u32 v4, v4, 6, 1
	v_and_b32_e32 v52, 0xffffff80, v49
	v_and_b32_e32 v37, 0x7e, v37
	v_and_b32_e32 v53, 0xffffff80, v50
	v_and_b32_e32 v39, 0x7e, v39
	v_or3_b32 v9, v12, v41, v33
	v_or3_b32 v54, v13, v43, v35
	v_cndmask_b32_e32 v6, v25, v6, vcc
	v_cndmask_b32_e32 v8, v29, v8, vcc
	v_mad_i64_i32 v[12:13], s[2:3], v7, s10, v[10:11]
	v_mad_i64_i32 v[22:23], s[2:3], v22, s10, v[10:11]
	v_mad_i64_i32 v[24:25], s[2:3], v24, s10, v[10:11]
	v_mad_i64_i32 v[26:27], s[2:3], v26, s10, v[10:11]
	v_mad_i64_i32 v[28:29], s[2:3], v28, s10, v[10:11]
	v_mad_i64_i32 v[30:31], s[2:3], v30, s10, v[10:11]
	v_mad_i64_i32 v[32:33], s[2:3], v32, s10, v[10:11]
	v_or3_b32 v52, v14, v52, v37
	v_or3_b32 v53, v4, v53, v39
	v_cndmask_b32_e32 v4, v21, v5, vcc
	v_mad_i64_i32 v[14:15], s[2:3], v15, s10, v[10:11]
	v_mad_i64_i32 v[16:17], s[2:3], v16, s10, v[10:11]
	v_mad_i64_i32 v[20:21], s[2:3], v20, s10, v[10:11]
	v_mad_i64_i32 v[34:35], s[2:3], v34, s10, v[10:11]
	v_mad_i64_i32 v[36:37], s[2:3], v36, s10, v[10:11]
	v_mad_i64_i32 v[38:39], s[2:3], v38, s10, v[10:11]
	v_mad_i64_i32 v[40:41], s[2:3], v40, s10, v[10:11]
	v_mad_i64_i32 v[42:43], s[2:3], v42, s10, v[10:11]
	v_mad_i64_i32 v[10:11], s[2:3], v45, s10, v[10:11]
	global_load_dword v45, v[12:13], off
	global_load_dword v55, v[14:15], off
	global_load_dword v56, v[16:17], off
	global_load_dword v57, v[20:21], off
	s_nop 0
	global_load_dword v22, v[22:23], off
	s_nop 0
	global_load_dword v23, v[24:25], off
	s_nop 0
	global_load_dword v24, v[26:27], off
	global_load_dword v25, v[28:29], off
	s_nop 0
	global_load_dword v26, v[30:31], off
	global_load_dword v27, v[32:33], off
	global_load_dword v28, v[34:35], off
	global_load_dword v29, v[36:37], off
	s_nop 0
	global_load_dword v30, v[38:39], off
	global_load_dword v31, v[40:41], off
	global_load_dword v32, v[42:43], off
	global_load_dword v33, v[10:11], off
	s_lshl_b32 s2, s8, 1
	v_cndmask_b32_e32 v10, v47, v9, vcc
	v_cndmask_b32_e32 v12, v48, v54, vcc
	v_cndmask_b32_e32 v14, v49, v52, vcc
	v_cndmask_b32_e32 v16, v50, v53, vcc
	s_add_u32 s2, s0, s2
	v_ashrrev_i32_e32 v3, 31, v2
	v_ashrrev_i32_e32 v5, 31, v4
	v_ashrrev_i32_e32 v7, 31, v6
	v_ashrrev_i32_e32 v9, 31, v8
	v_ashrrev_i32_e32 v11, 31, v10
	v_ashrrev_i32_e32 v13, 31, v12
	v_ashrrev_i32_e32 v15, 31, v14
	v_ashrrev_i32_e32 v17, 31, v16
	v_lshlrev_b32_e32 v0, 1, v44
	s_addc_u32 s3, s4, 0
	v_lshlrev_b64 v[2:3], 11, v[2:3]
	v_lshlrev_b64 v[4:5], 11, v[4:5]
	v_lshlrev_b64 v[6:7], 11, v[6:7]
	v_lshlrev_b64 v[8:9], 11, v[8:9]
	v_lshlrev_b64 v[10:11], 11, v[10:11]
	v_lshlrev_b64 v[12:13], 11, v[12:13]
	v_lshlrev_b64 v[14:15], 11, v[14:15]
	v_lshlrev_b64 v[16:17], 11, v[16:17]
	v_lshl_add_u64 v[20:21], s[2:3], 0, v[0:1]
	v_lshl_add_u64 v[2:3], v[20:21], 0, v[2:3]
	v_lshl_add_u64 v[4:5], v[20:21], 0, v[4:5]
	v_lshl_add_u64 v[6:7], v[20:21], 0, v[6:7]
	v_lshl_add_u64 v[8:9], v[20:21], 0, v[8:9]
	v_lshl_add_u64 v[10:11], v[20:21], 0, v[10:11]
	v_lshl_add_u64 v[12:13], v[20:21], 0, v[12:13]
	v_lshl_add_u64 v[14:15], v[20:21], 0, v[14:15]
	v_lshl_add_u64 v[16:17], v[20:21], 0, v[16:17]
	s_add_i32 s7, s7, s89
	s_add_i32 s5, s5, s6
	s_cmpk_gt_i32 s7, 0x1ff
	s_waitcnt vmcnt(15)
	v_mul_f32_e32 v0, v19, v45
	s_waitcnt vmcnt(14)
	v_mul_f32_e32 v20, v19, v55
	s_waitcnt vmcnt(13)
	v_mul_f32_e32 v21, v19, v56
	s_waitcnt vmcnt(12)
	v_mul_f32_e32 v34, v19, v57
	s_waitcnt vmcnt(11)
	v_mul_f32_e32 v22, v19, v22
	s_waitcnt vmcnt(10)
	v_mul_f32_e32 v23, v19, v23
	s_waitcnt vmcnt(9)
	v_mul_f32_e32 v24, v19, v24
	s_waitcnt vmcnt(8)
	v_mul_f32_e32 v25, v19, v25
	s_waitcnt vmcnt(7)
	v_mul_f32_e32 v26, v19, v26
	s_waitcnt vmcnt(6)
	v_mul_f32_e32 v27, v19, v27
	s_waitcnt vmcnt(5)
	v_mul_f32_e32 v28, v19, v28
	s_waitcnt vmcnt(4)
	v_mul_f32_e32 v29, v19, v29
	s_waitcnt vmcnt(3)
	v_mul_f32_e32 v30, v19, v30
	s_waitcnt vmcnt(2)
	v_mul_f32_e32 v31, v19, v31
	s_waitcnt vmcnt(1)
	v_mul_f32_e32 v32, v19, v32
	s_waitcnt vmcnt(0)
	v_mul_f32_e32 v19, v19, v33
	ds_write_b32 v46, v0
	ds_write_b32 v46, v20 offset:2064
	ds_write_b32 v46, v21 offset:4128
	ds_write_b32 v46, v34 offset:6192
	ds_write_b32 v46, v22 offset:8256
	ds_write_b32 v46, v23 offset:10320
	ds_write_b32 v46, v24 offset:12384
	ds_write_b32 v46, v25 offset:14448
	ds_write_b32 v46, v26 offset:16512
	ds_write_b32 v46, v27 offset:18576
	ds_write_b32 v46, v28 offset:20640
	ds_write_b32 v46, v29 offset:22704
	ds_write_b32 v46, v30 offset:24768
	ds_write_b32 v46, v31 offset:26832
	ds_write_b32 v46, v32 offset:28896
	ds_write_b32 v46, v19 offset:30960
	s_waitcnt lgkmcnt(0)
	s_barrier
; __device__ __forceinline__ unsigned cvt_pk_bf16(float lo, float hi) { unsigned r; asm volatile("v_cvt_pk_bf16_f32 %0, %1, %2" : "=v"(r) : "v"(lo), "v"(hi)); return r; }
; __device__ void wt_tile(const float* src, int ld, int k0, int n0, bf16_t* dst, int Kdst, const float* kscale, float mul, LAS float* tile, bool rotperm = false, int drow0 = -1) {
;     ...
;     for (int i = 0; i < 8; ++i) { const int n = (tid >> 5) + 16 * i, k2 = (tid & 31) * 2;
;         const float a = tile[k2 * 129 + n], b = tile[(k2 + 1) * 129 + n]; int nn = (drow0 >= 0 ? drow0 : n0) + n; if (rotperm) nn = (nn & ~127) | (2 * (nn & 63) + ((nn >> 6) & 1));
;         *(unsigned*)(dst + (size_t)nn * Kdst + k0 + k2) = cvt_pk_bf16(a, b); }
;     __syncthreads();
	ds_read2_b32 v[116:117], v51 offset1:129
	ds_read2_b32 v[118:119], v51 offset0:16 offset1:145
	ds_read2_b32 v[120:121], v51 offset0:32 offset1:161
	ds_read2_b32 v[122:123], v51 offset0:48 offset1:177
	ds_read2_b32 v[124:125], v51 offset0:64 offset1:193
	ds_read2_b32 v[126:127], v51 offset0:80 offset1:209
	ds_read2_b32 v[128:129], v51 offset0:96 offset1:225
	ds_read2_b32 v[130:131], v51 offset0:112 offset1:241
	s_waitcnt lgkmcnt(7)
	v_cvt_pk_bf16_f32 v0, v116, v117
	global_store_dword v[2:3], v0, off
	s_waitcnt lgkmcnt(6)
	v_cvt_pk_bf16_f32 v0, v118, v119
	global_store_dword v[4:5], v0, off
	s_waitcnt lgkmcnt(5)
	v_cvt_pk_bf16_f32 v0, v120, v121
	global_store_dword v[6:7], v0, off
	s_waitcnt lgkmcnt(4)
	v_cvt_pk_bf16_f32 v0, v122, v123
	global_store_dword v[8:9], v0, off
	s_waitcnt lgkmcnt(3)
	v_cvt_pk_bf16_f32 v0, v124, v125
	global_store_dword v[10:11], v0, off
	s_waitcnt lgkmcnt(2)
	v_cvt_pk_bf16_f32 v0, v126, v127
	global_store_dword v[12:13], v0, off
	s_waitcnt lgkmcnt(1)
	v_cvt_pk_bf16_f32 v0, v128, v129
	global_store_dword v[14:15], v0, off
	s_waitcnt lgkmcnt(0)
	v_cvt_pk_bf16_f32 v0, v130, v131
	global_store_dword v[16:17], v0, off
	s_barrier
	s_cbranch_scc0 .LBB0_1041
